# S5 pass2 epilogue: hoist the 4 per-subchunk u loads above the f32-MFMA section, counted vmcnt(3) instead of vmcnt(0) per element
# speedup vs baseline: 1.0064x; 1.0026x over previous
; __device__ __forceinline__ void s5_bu16(const S5Frag& f, const bf16x8 uf, float* buL, int lane) {
;     const int jj = lane & 15, quad = lane >> 4;
; #pragma unroll
;     for (int nt = 0; nt < 4; ++nt) {
;         const f32x4 z = (f32x4){0.f, 0.f, 0.f, 0.f};
;         const f32x4 dre = __builtin_amdgcn_mfma_f32_16x16x32_bf16(uf, f.bfr[nt], z, 0, 0, 0);
;         const f32x4 dim = __builtin_amdgcn_mfma_f32_16x16x32_bf16(uf, f.bfr[nt + 4], z, 0, 0, 0);
; #pragma unroll
;         for (int r = 0; r < 4; ++r) *(f32x2*)(buL + ((4 * quad + r) * 64 + 16 * nt + jj) * 2) = (f32x2){dre[r], dim[r]};
;     }
; }
; __device__ __forceinline__ void s5_pass2_item(PP p, unsigned char* shm, int item, int l) {
;     ...
;     const float dsk = p->in[13][(size_t)l * 512 + g * 16 + cc];
;     bf16_t* Gout = (bf16_t*)(p->ws + WS_GPH);
;     for (int sc = 0; sc < 4; ++sc) {
;         s5_bu16(f, uf[sc], buL, lane);
;         __syncthreads();
; #pragma unroll
;         for (int t = 0; t < 16; ++t) { s5_rec(q, *(const f32x2*)(buL + (t * 64 + lane) * 2), x); xs[t * 132 + lane] = x.x; xs[t * 132 + 64 + lane] = x.y; }
.LBB0_679:
	s_or_b64 exec, exec, s[2:3]
	s_movk_i32 s2, 0x2100
	v_mul_lo_u32 v0, v93, s2
	s_add_i32 s2, 0, 0x11000
	v_add_u32_e32 v102, s2, v0
	s_load_dwordx2 s[2:3], s[12:13], 0x68
	v_lshl_add_u32 v0, v93, 13, 0
	v_mul_f32_e32 v77, v77, v97
	v_mul_f32_e32 v76, v76, v97
	v_mul_f32_e32 v75, v75, v97
	s_waitcnt lgkmcnt(0)
	s_add_u32 s12, s2, s18
	s_addc_u32 s13, s3, 0
	s_lshl_b64 s[2:3], s[34:35], 2
	s_add_u32 s2, s12, s2
	v_mul_f32_e32 v74, v74, v97
	v_mul_f32_e32 v73, v73, v97
	v_mul_f32_e32 v72, v72, v97
	v_mul_f32_e32 v71, v71, v97
	v_mul_f32_e32 v70, v70, v97
	v_mul_f32_e32 v69, v69, v97
	v_mul_f32_e32 v68, v68, v97
	v_mul_f32_e32 v67, v67, v97
	v_mul_f32_e32 v66, v66, v97
	v_mul_f32_e32 v65, v65, v97
	v_mul_f32_e32 v64, v64, v97
	v_mul_f32_e32 v63, v63, v97
	v_mul_f32_e32 v62, v62, v97
	v_mul_f32_e32 v61, v61, v97
	v_mul_f32_e32 v60, v60, v97
	v_mul_f32_e32 v59, v59, v97
	v_mul_f32_e32 v58, v58, v97
	v_mul_f32_e32 v57, v57, v97
	v_mul_f32_e32 v56, v56, v97
	v_mul_f32_e32 v55, v55, v97
	v_mul_f32_e32 v85, v54, v97
	v_mul_f32_e32 v88, v53, v97
	v_mul_f32_e32 v91, v52, v97
	v_mul_f32_e32 v92, v51, v97
	v_mul_f32_e32 v93, v50, v97
	v_mul_f32_e32 v94, v49, v97
	v_mul_f32_e32 v95, v48, v97
	v_mul_f32_e32 v96, v47, v97
	v_mul_f32_e32 v97, v46, v97
	s_addc_u32 s3, s13, s3
	v_lshlrev_b32_e32 v46, 2, v100
	global_load_dword v54, v46, s[2:3]
	v_and_b32_e32 v46, 0x600, v99
	v_lshl_add_u32 v46, v46, 2, v0
	v_and_b32_e32 v47, 0x78, v90
	v_add_u32_e32 v108, v46, v47
	v_or_b32_e32 v47, 0x180, v90
	v_add_u32_e32 v99, v46, v47
	v_mul_u32_u24_e32 v46, 0x210, v100
	v_lshlrev_b32_e32 v47, 2, v101
	v_add_u32_e32 v90, v0, v90
	v_mov_b32_e32 v0, v89
	v_lshl_add_u32 v98, v98, 2, v102
	v_add3_u32 v89, v102, v46, v47
	v_or_b32_e32 v50, s34, v100
	v_mfma_f32_16x16x32_bf16 v[46:49], v[78:81], v[26:29], 0
	v_add_u32_e32 v108, 0x1000, v108
	v_lshl_or_b32 v82, v109, 2, v82
	v_mov_b32_e32 v51, s35
	v_mfma_f32_16x16x32_bf16 v[100:103], v[78:81], v[34:37], 0
	s_add_u32 s28, s28, 0x21600000
	s_nop 2
	v_mov_b32_e32 v52, v46
	v_mov_b32_e32 v110, v48
	v_mfma_f32_16x16x32_bf16 v[104:107], v[78:81], v[30:33], 0
	s_addc_u32 s29, s29, 0
	v_mov_b32_e32 v53, v100
	v_mov_b32_e32 v100, v47
	v_mov_b32_e32 v111, v102
	v_mov_b32_e32 v102, v49
	v_mfma_f32_16x16x32_bf16 v[46:49], v[78:81], v[22:25], 0
	s_nop 1
	v_mov_b32_e32 v113, v104
	s_add_i32 s14, s14, s66
	s_cmpk_gt_i32 s14, 0x1ff
	s_nop 2
	v_mov_b32_e32 v112, v46
	v_mov_b32_e32 v104, v47
	v_mov_b32_e32 v46, v48
	v_mov_b32_e32 v47, v106
	ds_write2_b64 v108, v[52:53], v[112:113] offset1:16
	ds_write2_b64 v108, v[110:111], v[46:47] offset0:128 offset1:144
	v_mov_b32_e32 v106, v49
	v_mfma_f32_16x16x32_bf16 v[46:49], v[78:81], v[18:21], 0
	v_mfma_f32_16x16x32_bf16 v[110:113], v[78:81], v[14:17], 0
	s_nop 6
	v_mov_b32_e32 v52, v46
	v_mov_b32_e32 v53, v110
	v_mov_b32_e32 v110, v47
	v_mov_b32_e32 v46, v48
	v_mov_b32_e32 v47, v112
	ds_write2_b64 v108, v[46:47], v[102:103] offset0:160 offset1:192
	v_mov_b32_e32 v112, v49
	v_mfma_f32_16x16x32_bf16 v[46:49], v[78:81], v[10:13], 0
	ds_write2_b64 v108, v[52:53], v[100:101] offset0:32 offset1:64
	ds_write2_b64 v108, v[104:105], v[110:111] offset0:80 offset1:96
	ds_write2_b64 v108, v[106:107], v[112:113] offset0:208 offset1:224
	v_mfma_f32_16x16x32_bf16 v[78:81], v[78:81], v[6:9], 0
	v_add_u32_e32 v100, 0x80, v98
	s_nop 2
	v_mov_b32_e32 v52, v46
	v_mov_b32_e32 v46, v48
	v_xor_b32_e32 v48, 0x80000000, v87
	v_add_u32_e32 v101, 0x90, v98
	v_mov_b32_e32 v53, v78
	v_mov_b32_e32 v78, v47
	v_mov_b32_e32 v47, v80
	v_mov_b32_e32 v80, v49
	ds_write2st64_b64 v99, v[52:53], v[78:79] offset0:8 offset1:9
	ds_write2st64_b64 v99, v[46:47], v[80:81] offset0:10 offset1:11
	s_waitcnt lgkmcnt(0)
	s_barrier
	ds_read_b64 v[46:47], v90 offset:4096
	v_mov_b32_e32 v49, v86
	v_pk_mul_f32 v[48:49], v[0:1], v[48:49] op_sel_hi:[0,1]
	v_pk_fma_f32 v[48:49], v[84:85], v[86:87], v[48:49] op_sel_hi:[0,1,1]
	v_add_u32_e32 v78, 32, v98
	s_waitcnt lgkmcnt(0)
	v_pk_add_f32 v[46:47], v[48:49], v[46:47]
	ds_write2st64_b32 v98, v46, v47 offset1:1
	ds_read_b64 v[48:49], v90 offset:4608
	v_xor_b32_e32 v52, 0x80000000, v47
	v_mov_b32_e32 v53, v46
	v_pk_mul_f32 v[52:53], v[0:1], v[52:53] op_sel_hi:[0,1]
	v_pk_fma_f32 v[46:47], v[84:85], v[46:47], v[52:53] op_sel_hi:[0,1,1]
	s_waitcnt lgkmcnt(0)
	v_pk_add_f32 v[46:47], v[48:49], v[46:47]
	ds_write2_b32 v98, v46, v47 offset0:132 offset1:196
	ds_read_b64 v[48:49], v90 offset:5120
	v_xor_b32_e32 v52, 0x80000000, v47
	v_mov_b32_e32 v53, v46
	v_pk_mul_f32 v[52:53], v[0:1], v[52:53] op_sel_hi:[0,1]
	v_pk_fma_f32 v[46:47], v[84:85], v[46:47], v[52:53] op_sel_hi:[0,1,1]
	s_waitcnt lgkmcnt(0)
	v_pk_add_f32 v[46:47], v[48:49], v[46:47]
	ds_write2st64_b32 v78, v46, v47 offset0:4 offset1:5
	ds_read_b64 v[48:49], v90 offset:5632
	v_xor_b32_e32 v52, 0x80000000, v47
	v_mov_b32_e32 v53, v46
	v_pk_mul_f32 v[52:53], v[0:1], v[52:53] op_sel_hi:[0,1]
	v_pk_fma_f32 v[46:47], v[84:85], v[46:47], v[52:53] op_sel_hi:[0,1,1]
	s_waitcnt lgkmcnt(0)
	v_pk_add_f32 v[46:47], v[48:49], v[46:47]
	v_add_u32_e32 v79, 48, v98
	ds_write2st64_b32 v79, v46, v47 offset0:6 offset1:7
	ds_read_b64 v[48:49], v90 offset:6144
	v_xor_b32_e32 v52, 0x80000000, v47
	v_mov_b32_e32 v53, v46
	v_pk_mul_f32 v[52:53], v[0:1], v[52:53] op_sel_hi:[0,1]
	v_pk_fma_f32 v[46:47], v[84:85], v[46:47], v[52:53] op_sel_hi:[0,1,1]
	s_waitcnt lgkmcnt(0)
	v_pk_add_f32 v[46:47], v[48:49], v[46:47]
	v_add_u32_e32 v80, 64, v98
	ds_write2st64_b32 v80, v46, v47 offset0:8 offset1:9
	ds_read_b64 v[48:49], v90 offset:6656
	v_xor_b32_e32 v52, 0x80000000, v47
	v_mov_b32_e32 v53, v46
	v_pk_mul_f32 v[52:53], v[0:1], v[52:53] op_sel_hi:[0,1]
	v_pk_fma_f32 v[46:47], v[84:85], v[46:47], v[52:53] op_sel_hi:[0,1,1]
	s_waitcnt lgkmcnt(0)
; __device__ __forceinline__ float bf2f(bf16_t v) { return __uint_as_float(((unsigned)v) << 16); }
; __device__ __forceinline__ void s5_pass2_item(PP p, unsigned char* shm, int item, int l) {
;     ...
;         for (int t = 0; t < 16; ++t) { s5_rec(q, *(const f32x2*)(buL + (t * 64 + lane) * 2), x); xs[t * 132 + lane] = x.x; xs[t * 132 + 64 + lane] = x.y; }
;         __syncthreads();
;         f32x4 y0 = (f32x4){0.f, 0.f, 0.f, 0.f}, y1 = y0;
;         const f32x4* xrow = (const f32x4*)(xs + cc * 132 + quad * 32);
; #pragma unroll
;         for (int i = 0; i < 8; ++i) { const f32x4 xv = xrow[i];
;             y0 = __builtin_amdgcn_mfma_f32_16x16x4f32(xv[0], cmr[4 * i + 0], y0, 0, 0, 0);
;             y1 = __builtin_amdgcn_mfma_f32_16x16x4f32(xv[1], cmr[4 * i + 1], y1, 0, 0, 0);
;             y0 = __builtin_amdgcn_mfma_f32_16x16x4f32(xv[2], cmr[4 * i + 2], y0, 0, 0, 0);
;             y1 = __builtin_amdgcn_mfma_f32_16x16x4f32(xv[3], cmr[4 * i + 3], y1, 0, 0, 0); }
;         const f32x4 y = y0 + y1;
; #pragma unroll
;         for (int r = 0; r < 4; ++r) { const int tl = sc * 16 + quad * 4 + r;
;             const float v = y[r] + dsk * bf2f(proj[PJ_UA + (row0 + tl) * 512 + g * 16 + cc]);
	v_pk_add_f32 v[46:47], v[48:49], v[46:47]
	v_add_u32_e32 v81, 0x50, v98
	ds_write2st64_b32 v81, v46, v47 offset0:10 offset1:11
	ds_read_b64 v[48:49], v90 offset:7168
	v_xor_b32_e32 v52, 0x80000000, v47
	v_mov_b32_e32 v53, v46
	v_pk_mul_f32 v[52:53], v[0:1], v[52:53] op_sel_hi:[0,1]
	v_pk_fma_f32 v[46:47], v[84:85], v[46:47], v[52:53] op_sel_hi:[0,1,1]
	s_waitcnt lgkmcnt(0)
	v_pk_add_f32 v[46:47], v[48:49], v[46:47]
	v_add_u32_e32 v86, 0x60, v98
	ds_write2st64_b32 v86, v46, v47 offset0:12 offset1:13
	ds_read_b64 v[48:49], v90 offset:7680
	v_xor_b32_e32 v52, 0x80000000, v47
	v_mov_b32_e32 v53, v46
	v_pk_mul_f32 v[52:53], v[0:1], v[52:53] op_sel_hi:[0,1]
	v_pk_fma_f32 v[46:47], v[84:85], v[46:47], v[52:53] op_sel_hi:[0,1,1]
	s_waitcnt lgkmcnt(0)
	v_pk_add_f32 v[46:47], v[48:49], v[46:47]
	v_add_u32_e32 v87, 0x70, v98
	ds_write2st64_b32 v87, v46, v47 offset0:14 offset1:15
	ds_read_b64 v[48:49], v90 offset:8192
	v_xor_b32_e32 v52, 0x80000000, v47
	v_mov_b32_e32 v53, v46
	v_pk_mul_f32 v[52:53], v[0:1], v[52:53] op_sel_hi:[0,1]
	v_pk_fma_f32 v[46:47], v[84:85], v[46:47], v[52:53] op_sel_hi:[0,1,1]
	s_waitcnt lgkmcnt(0)
	v_pk_add_f32 v[46:47], v[48:49], v[46:47]
	ds_write2st64_b32 v100, v46, v47 offset0:16 offset1:17
	ds_read_b64 v[48:49], v90 offset:8704
	v_xor_b32_e32 v52, 0x80000000, v47
	v_mov_b32_e32 v53, v46
	v_pk_mul_f32 v[52:53], v[0:1], v[52:53] op_sel_hi:[0,1]
	v_pk_fma_f32 v[46:47], v[84:85], v[46:47], v[52:53] op_sel_hi:[0,1,1]
	s_waitcnt lgkmcnt(0)
	v_pk_add_f32 v[46:47], v[48:49], v[46:47]
	ds_write2st64_b32 v101, v46, v47 offset0:18 offset1:19
	ds_read_b64 v[48:49], v90 offset:9216
	v_xor_b32_e32 v52, 0x80000000, v47
	v_mov_b32_e32 v53, v46
	v_pk_mul_f32 v[52:53], v[0:1], v[52:53] op_sel_hi:[0,1]
	v_pk_fma_f32 v[46:47], v[84:85], v[46:47], v[52:53] op_sel_hi:[0,1,1]
	s_waitcnt lgkmcnt(0)
	v_pk_add_f32 v[46:47], v[48:49], v[46:47]
	v_add_u32_e32 v102, 0xa0, v98
	ds_write2st64_b32 v102, v46, v47 offset0:20 offset1:21
	ds_read_b64 v[48:49], v90 offset:9728
	v_xor_b32_e32 v52, 0x80000000, v47
	v_mov_b32_e32 v53, v46
	v_pk_mul_f32 v[52:53], v[0:1], v[52:53] op_sel_hi:[0,1]
	v_pk_fma_f32 v[46:47], v[84:85], v[46:47], v[52:53] op_sel_hi:[0,1,1]
	s_waitcnt lgkmcnt(0)
	v_pk_add_f32 v[46:47], v[48:49], v[46:47]
	v_add_u32_e32 v103, 0xb0, v98
	ds_write2st64_b32 v103, v46, v47 offset0:22 offset1:23
	ds_read_b64 v[48:49], v90 offset:10240
	v_xor_b32_e32 v52, 0x80000000, v47
	v_mov_b32_e32 v53, v46
	v_pk_mul_f32 v[52:53], v[0:1], v[52:53] op_sel_hi:[0,1]
	v_pk_fma_f32 v[46:47], v[84:85], v[46:47], v[52:53] op_sel_hi:[0,1,1]
	s_waitcnt lgkmcnt(0)
	v_pk_add_f32 v[46:47], v[48:49], v[46:47]
	v_add_u32_e32 v104, 0xc0, v98
	ds_write2st64_b32 v104, v46, v47 offset0:24 offset1:25
	ds_read_b64 v[48:49], v90 offset:10752
	v_xor_b32_e32 v52, 0x80000000, v47
	v_mov_b32_e32 v53, v46
	v_pk_mul_f32 v[52:53], v[0:1], v[52:53] op_sel_hi:[0,1]
	v_pk_fma_f32 v[46:47], v[84:85], v[46:47], v[52:53] op_sel_hi:[0,1,1]
	s_waitcnt lgkmcnt(0)
	v_pk_add_f32 v[46:47], v[48:49], v[46:47]
	v_add_u32_e32 v105, 0xd0, v98
	ds_write2st64_b32 v105, v46, v47 offset0:26 offset1:27
	ds_read_b64 v[48:49], v90 offset:11264
	v_xor_b32_e32 v52, 0x80000000, v47
	v_mov_b32_e32 v53, v46
	v_pk_mul_f32 v[52:53], v[0:1], v[52:53] op_sel_hi:[0,1]
	v_pk_fma_f32 v[46:47], v[84:85], v[46:47], v[52:53] op_sel_hi:[0,1,1]
	s_waitcnt lgkmcnt(0)
	v_pk_add_f32 v[46:47], v[48:49], v[46:47]
	v_add_u32_e32 v106, 0xe0, v98
	ds_write2st64_b32 v106, v46, v47 offset0:28 offset1:29
	ds_read_b64 v[48:49], v90 offset:11776
	v_xor_b32_e32 v52, 0x80000000, v47
	v_mov_b32_e32 v53, v46
	v_pk_mul_f32 v[52:53], v[0:1], v[52:53] op_sel_hi:[0,1]
	v_pk_fma_f32 v[46:47], v[84:85], v[46:47], v[52:53] op_sel_hi:[0,1,1]
	s_waitcnt lgkmcnt(0)
	v_pk_add_f32 v[52:53], v[48:49], v[46:47]
	v_add_u32_e32 v107, 0xf0, v98
	ds_write2st64_b32 v107, v52, v53 offset0:30 offset1:31
	s_waitcnt lgkmcnt(0)
	s_barrier
	v_mov_b32_e32 v216, v82
	v_mov_b32_e32 v217, v83
	v_lshlrev_b64 v[216:217], 9, v[216:217]
	v_lshl_add_u64 v[216:217], v[216:217], 0, v[50:51]
	v_lshlrev_b64 v[216:217], 1, v[216:217]
	v_lshl_add_u64 v[216:217], s[8:9], 0, v[216:217]
	global_load_ushort v200, v[216:217], off
	global_load_ushort v201, v[216:217], off offset:1024
	global_load_ushort v202, v[216:217], off offset:2048
	global_load_ushort v203, v[216:217], off offset:3072
	ds_read_b128 v[46:49], v89
	ds_read_b128 v[110:113], v89 offset:16
	ds_read_b128 v[114:117], v89 offset:32
	ds_read_b128 v[118:121], v89 offset:48
	s_waitcnt lgkmcnt(3)
	v_mfma_f32_16x16x4_f32 v[122:125], v46, v97, 0
	v_mfma_f32_16x16x4_f32 v[126:129], v47, v96, 0
	v_mfma_f32_16x16x4_f32 v[122:125], v48, v95, v[122:125]
	v_mfma_f32_16x16x4_f32 v[46:49], v49, v94, v[126:129]
	s_waitcnt lgkmcnt(2)
	v_mfma_f32_16x16x4_f32 v[122:125], v110, v93, v[122:125]
	v_mfma_f32_16x16x4_f32 v[46:49], v111, v92, v[46:49]
	v_mfma_f32_16x16x4_f32 v[122:125], v112, v91, v[122:125]
	v_mfma_f32_16x16x4_f32 v[46:49], v113, v88, v[46:49]
	s_waitcnt lgkmcnt(1)
	v_mfma_f32_16x16x4_f32 v[110:113], v114, v85, v[122:125]
	v_mfma_f32_16x16x4_f32 v[46:49], v115, v55, v[46:49]
	v_mfma_f32_16x16x4_f32 v[110:113], v116, v56, v[110:113]
	v_mfma_f32_16x16x4_f32 v[46:49], v117, v57, v[46:49]
	ds_read_b128 v[114:117], v89 offset:64
	s_waitcnt lgkmcnt(1)
	v_mfma_f32_16x16x4_f32 v[110:113], v118, v58, v[110:113]
	v_mfma_f32_16x16x4_f32 v[46:49], v119, v59, v[46:49]
	v_mfma_f32_16x16x4_f32 v[110:113], v120, v60, v[110:113]
	v_mfma_f32_16x16x4_f32 v[46:49], v121, v61, v[46:49]
	s_waitcnt lgkmcnt(0)
; __device__ __forceinline__ float bf2f(bf16_t v) { return __uint_as_float(((unsigned)v) << 16); }
; __device__ __forceinline__ bf16_t f2bf(float f) { unsigned u = __float_as_uint(f); u += 0x7FFFu + ((u >> 16) & 1u); return (bf16_t)(u >> 16); }
; __device__ __forceinline__ void s5_pass2_item(PP p, unsigned char* shm, int item, int l) {
;     ...
;         const f32x4 y = y0 + y1;
; #pragma unroll
;         for (int r = 0; r < 4; ++r) { const int tl = sc * 16 + quad * 4 + r;
;             const float v = y[r] + dsk * bf2f(proj[PJ_UA + (row0 + tl) * 512 + g * 16 + cc]);
;             const float z = 0.7978845608028654f * (v + 0.044715f * v * v * v);
;             const float th = 1.0f - 2.0f / (__expf(2.0f * z) + 1.0f);
;             Gout[(row0 + tl) * 512 + g * 16 + cc] = f2bf(0.5f * v * (1.0f + th)); }
	v_mfma_f32_16x16x4_f32 v[110:113], v114, v62, v[110:113]
	v_mfma_f32_16x16x4_f32 v[46:49], v115, v63, v[46:49]
	v_mfma_f32_16x16x4_f32 v[110:113], v116, v64, v[110:113]
	v_mfma_f32_16x16x4_f32 v[46:49], v117, v65, v[46:49]
	ds_read_b128 v[114:117], v89 offset:80
	s_waitcnt lgkmcnt(0)
	v_mfma_f32_16x16x4_f32 v[110:113], v114, v66, v[110:113]
	v_mfma_f32_16x16x4_f32 v[46:49], v115, v67, v[46:49]
	v_mfma_f32_16x16x4_f32 v[110:113], v116, v68, v[110:113]
	v_mfma_f32_16x16x4_f32 v[46:49], v117, v69, v[46:49]
	ds_read_b128 v[114:117], v89 offset:96
	s_waitcnt lgkmcnt(0)
	v_mfma_f32_16x16x4_f32 v[110:113], v114, v70, v[110:113]
	v_mfma_f32_16x16x4_f32 v[46:49], v115, v71, v[46:49]
	v_mfma_f32_16x16x4_f32 v[110:113], v116, v72, v[110:113]
	v_mfma_f32_16x16x4_f32 v[46:49], v117, v73, v[46:49]
	ds_read_b128 v[114:117], v89 offset:112
	s_waitcnt lgkmcnt(0)
	v_mfma_f32_16x16x4_f32 v[110:113], v114, v74, v[110:113]
	v_mfma_f32_16x16x4_f32 v[46:49], v115, v75, v[46:49]
	v_mfma_f32_16x16x4_f32 v[110:113], v116, v76, v[110:113]
	v_mfma_f32_16x16x4_f32 v[46:49], v117, v77, v[46:49]
	s_nop 9
	v_pk_add_f32 v[46:47], v[110:111], v[46:47]
	v_lshlrev_b64 v[110:111], 9, v[82:83]
	v_lshl_add_u64 v[110:111], v[110:111], 0, v[50:51]
	v_lshlrev_b64 v[110:111], 1, v[110:111]
	v_pk_add_f32 v[48:49], v[112:113], v[48:49]
	v_lshl_add_u64 v[112:113], s[8:9], 0, v[110:111]
	v_lshl_add_u64 v[110:111], s[28:29], 0, v[110:111]
	s_waitcnt vmcnt(3)
	v_lshlrev_b32_e32 v109, 16, v200
	v_fma_f32 v46, v54, v109, v46
	v_mul_f32_e32 v109, 0x3d372713, v46
	v_mul_f32_e32 v109, v46, v109
	v_fma_f32 v109, v46, v109, v46
	v_mul_f32_e32 v109, 0x3f4c422a, v109
	v_add_f32_e32 v109, v109, v109
	v_mul_f32_e32 v109, 0x3fb8aa3b, v109
	v_exp_f32_e32 v109, v109
	v_mul_f32_e32 v46, 0.5, v46
	v_add_f32_e32 v109, 1.0, v109
	v_div_scale_f32 v112, s[2:3], v109, v109, 2.0
	v_rcp_f32_e32 v113, v112
	s_nop 0
	v_fma_f32 v114, -v112, v113, 1.0
	v_fmac_f32_e32 v113, v114, v113
	v_div_scale_f32 v114, vcc, 2.0, v109, 2.0
	v_mul_f32_e32 v115, v114, v113
	v_fma_f32 v116, -v112, v115, v114
	v_fmac_f32_e32 v115, v116, v113
	v_fma_f32 v112, -v112, v115, v114
	v_div_fmas_f32 v112, v112, v113, v115
	v_div_fixup_f32 v109, v112, v109, 2.0
	v_sub_f32_e32 v109, 1.0, v109
	v_add_f32_e32 v109, 1.0, v109
	v_mul_f32_e32 v46, v46, v109
	v_bfe_u32 v109, v46, 16, 1
	v_add3_u32 v46, v46, v109, s31
	global_store_short_d16_hi v[110:111], v46, off
	v_or_b32_e32 v110, 1, v82
	v_mov_b32_e32 v111, v83
	v_lshlrev_b64 v[110:111], 9, v[110:111]
	v_lshl_add_u64 v[110:111], v[110:111], 0, v[50:51]
	v_lshlrev_b64 v[110:111], 1, v[110:111]
	v_lshl_add_u64 v[112:113], s[8:9], 0, v[110:111]
	s_waitcnt vmcnt(3)
	v_lshlrev_b32_e32 v46, 16, v201
	v_fmac_f32_e32 v47, v54, v46
	v_mul_f32_e32 v46, 0x3d372713, v47
	v_mul_f32_e32 v46, v47, v46
	v_fma_f32 v46, v47, v46, v47
	v_mul_f32_e32 v46, 0x3f4c422a, v46
	v_add_f32_e32 v46, v46, v46
	v_mul_f32_e32 v46, 0x3fb8aa3b, v46
	v_exp_f32_e32 v46, v46
	v_mul_f32_e32 v47, 0.5, v47
	v_add_f32_e32 v46, 1.0, v46
	v_div_scale_f32 v109, s[2:3], v46, v46, 2.0
	v_rcp_f32_e32 v112, v109
	s_nop 0
	v_fma_f32 v113, -v109, v112, 1.0
	v_fmac_f32_e32 v112, v113, v112
	v_div_scale_f32 v113, vcc, 2.0, v46, 2.0
	v_mul_f32_e32 v114, v113, v112
	v_fma_f32 v115, -v109, v114, v113
	v_fmac_f32_e32 v114, v115, v112
	v_fma_f32 v109, -v109, v114, v113
	v_div_fmas_f32 v109, v109, v112, v114
	v_div_fixup_f32 v46, v109, v46, 2.0
	v_sub_f32_e32 v46, 1.0, v46
	v_add_f32_e32 v46, 1.0, v46
	v_mul_f32_e32 v46, v47, v46
	v_bfe_u32 v47, v46, 16, 1
	v_add3_u32 v109, v46, v47, s31
	v_lshl_add_u64 v[46:47], s[28:29], 0, v[110:111]
	global_store_short_d16_hi v[46:47], v109, off
	v_or_b32_e32 v46, 2, v82
	v_mov_b32_e32 v47, v83
	v_lshlrev_b64 v[46:47], 9, v[46:47]
	v_lshl_add_u64 v[46:47], v[46:47], 0, v[50:51]
	v_lshlrev_b64 v[46:47], 1, v[46:47]
	v_lshl_add_u64 v[110:111], s[8:9], 0, v[46:47]
	v_lshl_add_u64 v[46:47], s[28:29], 0, v[46:47]
	s_waitcnt vmcnt(3)
	v_lshlrev_b32_e32 v109, 16, v202
	v_fma_f32 v48, v54, v109, v48
	v_mul_f32_e32 v109, 0x3d372713, v48
	v_mul_f32_e32 v109, v48, v109
	v_fma_f32 v109, v48, v109, v48
	v_mul_f32_e32 v109, 0x3f4c422a, v109
	v_add_f32_e32 v109, v109, v109
	v_mul_f32_e32 v109, 0x3fb8aa3b, v109
	v_exp_f32_e32 v109, v109
	v_mul_f32_e32 v48, 0.5, v48
	v_add_f32_e32 v109, 1.0, v109
	v_div_scale_f32 v110, s[2:3], v109, v109, 2.0
	v_rcp_f32_e32 v111, v110
	s_nop 0
	v_fma_f32 v112, -v110, v111, 1.0
	v_fmac_f32_e32 v111, v112, v111
	v_div_scale_f32 v112, vcc, 2.0, v109, 2.0
	v_mul_f32_e32 v113, v112, v111
	v_fma_f32 v114, -v110, v113, v112
	v_fmac_f32_e32 v113, v114, v111
	v_fma_f32 v110, -v110, v113, v112
	v_div_fmas_f32 v110, v110, v111, v113
	v_div_fixup_f32 v109, v110, v109, 2.0
	v_sub_f32_e32 v109, 1.0, v109
	v_add_f32_e32 v109, 1.0, v109
	v_mul_f32_e32 v48, v48, v109
	v_bfe_u32 v109, v48, 16, 1
	v_add3_u32 v48, v48, v109, s31
	global_store_short_d16_hi v[46:47], v48, off
	v_or_b32_e32 v46, 3, v82
	v_mov_b32_e32 v47, v83
	v_lshlrev_b64 v[46:47], 9, v[46:47]
	v_lshl_add_u64 v[46:47], v[46:47], 0, v[50:51]
	v_lshlrev_b64 v[46:47], 1, v[46:47]
	v_lshl_add_u64 v[110:111], s[8:9], 0, v[46:47]
	v_lshl_add_u64 v[46:47], s[28:29], 0, v[46:47]
	v_mfma_f32_16x16x32_bf16 v[114:117], v[42:45], v[30:33], 0
	s_waitcnt vmcnt(3)
	v_lshlrev_b32_e32 v48, 16, v203
	v_fmac_f32_e32 v49, v54, v48
	v_mul_f32_e32 v48, 0x3d372713, v49
	v_mul_f32_e32 v48, v49, v48
	v_fma_f32 v48, v49, v48, v49
	v_mul_f32_e32 v48, 0x3f4c422a, v48
	v_add_f32_e32 v48, v48, v48
	v_mul_f32_e32 v48, 0x3fb8aa3b, v48
	v_exp_f32_e32 v48, v48
	v_mul_f32_e32 v49, 0.5, v49
	v_mov_b32_e32 v123, v114
	v_add_f32_e32 v48, 1.0, v48
	v_div_scale_f32 v109, s[2:3], v48, v48, 2.0
	v_rcp_f32_e32 v110, v109
	s_nop 0
	v_fma_f32 v111, -v109, v110, 1.0
	v_fmac_f32_e32 v110, v111, v110
	v_div_scale_f32 v111, vcc, 2.0, v48, 2.0
	v_mul_f32_e32 v112, v111, v110
	v_fma_f32 v113, -v109, v112, v111
	v_fmac_f32_e32 v112, v113, v110
	v_fma_f32 v109, -v109, v112, v111
	v_div_fmas_f32 v109, v109, v110, v112
	v_div_fixup_f32 v48, v109, v48, 2.0
	v_sub_f32_e32 v48, 1.0, v48
	v_add_f32_e32 v48, 1.0, v48
	v_mul_f32_e32 v48, v49, v48
	v_bfe_u32 v49, v48, 16, 1
	v_add3_u32 v48, v48, v49, s31
	global_store_short_d16_hi v[46:47], v48, off
	v_mfma_f32_16x16x32_bf16 v[46:49], v[42:45], v[26:29], 0
	s_barrier
; __device__ __forceinline__ void s5_bu16(const S5Frag& f, const bf16x8 uf, float* buL, int lane) {
;     const int jj = lane & 15, quad = lane >> 4;
; #pragma unroll
;     for (int nt = 0; nt < 4; ++nt) {
;         const f32x4 z = (f32x4){0.f, 0.f, 0.f, 0.f};
;         const f32x4 dre = __builtin_amdgcn_mfma_f32_16x16x32_bf16(uf, f.bfr[nt], z, 0, 0, 0);
;         const f32x4 dim = __builtin_amdgcn_mfma_f32_16x16x32_bf16(uf, f.bfr[nt + 4], z, 0, 0, 0);
; #pragma unroll
;         for (int r = 0; r < 4; ++r) *(f32x2*)(buL + ((4 * quad + r) * 64 + 16 * nt + jj) * 2) = (f32x2){dre[r], dim[r]};
;     }
; }
; __device__ __forceinline__ void s5_pass2_item(PP p, unsigned char* shm, int item, int l) {
;     ...
;     for (int sc = 0; sc < 4; ++sc) {
;         s5_bu16(f, uf[sc], buL, lane);
;         __syncthreads();
; #pragma unroll
;         for (int t = 0; t < 16; ++t) { s5_rec(q, *(const f32x2*)(buL + (t * 64 + lane) * 2), x); xs[t * 132 + lane] = x.x; xs[t * 132 + 64 + lane] = x.y; }
	v_mfma_f32_16x16x32_bf16 v[110:113], v[42:45], v[34:37], 0
	s_nop 5
	v_mov_b32_e32 v118, v46
	s_nop 0
	v_mov_b32_e32 v119, v110
	v_mov_b32_e32 v110, v47
	v_mov_b32_e32 v120, v48
	v_mov_b32_e32 v121, v112
	v_mov_b32_e32 v112, v49
	v_mfma_f32_16x16x32_bf16 v[46:49], v[42:45], v[22:25], 0
	s_nop 7
	v_mov_b32_e32 v122, v46
	v_mov_b32_e32 v114, v47
	v_mov_b32_e32 v46, v48
	v_mov_b32_e32 v47, v116
	ds_write2_b64 v108, v[118:119], v[122:123] offset1:16
	ds_write2_b64 v108, v[120:121], v[46:47] offset0:128 offset1:144
	v_mov_b32_e32 v116, v49
	v_mfma_f32_16x16x32_bf16 v[46:49], v[42:45], v[18:21], 0
	v_mfma_f32_16x16x32_bf16 v[118:121], v[42:45], v[14:17], 0
	s_nop 6
	v_mov_b32_e32 v122, v46
	v_mov_b32_e32 v123, v118
	v_mov_b32_e32 v118, v47
	v_mov_b32_e32 v46, v48
	v_mov_b32_e32 v47, v120
	ds_write2_b64 v108, v[46:47], v[112:113] offset0:160 offset1:192
	v_mov_b32_e32 v120, v49
	v_mfma_f32_16x16x32_bf16 v[46:49], v[42:45], v[10:13], 0
	ds_write2_b64 v108, v[122:123], v[110:111] offset0:32 offset1:64
	ds_write2_b64 v108, v[114:115], v[118:119] offset0:80 offset1:96
	ds_write2_b64 v108, v[116:117], v[120:121] offset0:208 offset1:224
	v_mfma_f32_16x16x32_bf16 v[42:45], v[42:45], v[6:9], 0
	s_nop 3
	v_mov_b32_e32 v110, v46
	s_nop 2
	v_mov_b32_e32 v111, v42
	v_mov_b32_e32 v42, v47
	ds_write2st64_b64 v99, v[110:111], v[42:43] offset0:8 offset1:9
	v_mov_b32_e32 v42, v48
	v_mov_b32_e32 v43, v44
	v_mov_b32_e32 v44, v49
	ds_write2st64_b64 v99, v[42:43], v[44:45] offset0:10 offset1:11
	s_waitcnt lgkmcnt(0)
	s_barrier
	ds_read_b64 v[42:43], v90 offset:4096
	v_xor_b32_e32 v44, 0x80000000, v53
	v_mov_b32_e32 v45, v52
	v_pk_mul_f32 v[44:45], v[0:1], v[44:45] op_sel_hi:[0,1]
	v_pk_fma_f32 v[44:45], v[84:85], v[52:53], v[44:45] op_sel_hi:[0,1,1]
	s_waitcnt lgkmcnt(0)
	v_pk_add_f32 v[42:43], v[44:45], v[42:43]
	ds_write2st64_b32 v98, v42, v43 offset1:1
	ds_read_b64 v[44:45], v90 offset:4608
	v_xor_b32_e32 v46, 0x80000000, v43
	v_mov_b32_e32 v47, v42
	v_pk_mul_f32 v[46:47], v[0:1], v[46:47] op_sel_hi:[0,1]
	v_pk_fma_f32 v[42:43], v[84:85], v[42:43], v[46:47] op_sel_hi:[0,1,1]
	s_waitcnt lgkmcnt(0)
	v_pk_add_f32 v[42:43], v[44:45], v[42:43]
	ds_write2_b32 v98, v42, v43 offset0:132 offset1:196
	ds_read_b64 v[44:45], v90 offset:5120
	v_xor_b32_e32 v46, 0x80000000, v43
	v_mov_b32_e32 v47, v42
	v_pk_mul_f32 v[46:47], v[0:1], v[46:47] op_sel_hi:[0,1]
	v_pk_fma_f32 v[42:43], v[84:85], v[42:43], v[46:47] op_sel_hi:[0,1,1]
	s_waitcnt lgkmcnt(0)
	v_pk_add_f32 v[42:43], v[44:45], v[42:43]
	ds_write2st64_b32 v78, v42, v43 offset0:4 offset1:5
	ds_read_b64 v[44:45], v90 offset:5632
	v_xor_b32_e32 v46, 0x80000000, v43
	v_mov_b32_e32 v47, v42
	v_pk_mul_f32 v[46:47], v[0:1], v[46:47] op_sel_hi:[0,1]
	v_pk_fma_f32 v[42:43], v[84:85], v[42:43], v[46:47] op_sel_hi:[0,1,1]
	s_waitcnt lgkmcnt(0)
	v_pk_add_f32 v[42:43], v[44:45], v[42:43]
	ds_write2st64_b32 v79, v42, v43 offset0:6 offset1:7
	ds_read_b64 v[44:45], v90 offset:6144
	v_xor_b32_e32 v46, 0x80000000, v43
	v_mov_b32_e32 v47, v42
	v_pk_mul_f32 v[46:47], v[0:1], v[46:47] op_sel_hi:[0,1]
	v_pk_fma_f32 v[42:43], v[84:85], v[42:43], v[46:47] op_sel_hi:[0,1,1]
	s_waitcnt lgkmcnt(0)
	v_pk_add_f32 v[42:43], v[44:45], v[42:43]
	ds_write2st64_b32 v80, v42, v43 offset0:8 offset1:9
	ds_read_b64 v[44:45], v90 offset:6656
	v_xor_b32_e32 v46, 0x80000000, v43
	v_mov_b32_e32 v47, v42
	v_pk_mul_f32 v[46:47], v[0:1], v[46:47] op_sel_hi:[0,1]
	v_pk_fma_f32 v[42:43], v[84:85], v[42:43], v[46:47] op_sel_hi:[0,1,1]
	s_waitcnt lgkmcnt(0)
	v_pk_add_f32 v[42:43], v[44:45], v[42:43]
	ds_write2st64_b32 v81, v42, v43 offset0:10 offset1:11
	ds_read_b64 v[44:45], v90 offset:7168
	v_xor_b32_e32 v46, 0x80000000, v43
	v_mov_b32_e32 v47, v42
	v_pk_mul_f32 v[46:47], v[0:1], v[46:47] op_sel_hi:[0,1]
	v_pk_fma_f32 v[42:43], v[84:85], v[42:43], v[46:47] op_sel_hi:[0,1,1]
	s_waitcnt lgkmcnt(0)
	v_pk_add_f32 v[42:43], v[44:45], v[42:43]
	ds_write2st64_b32 v86, v42, v43 offset0:12 offset1:13
	ds_read_b64 v[44:45], v90 offset:7680
	v_xor_b32_e32 v46, 0x80000000, v43
	v_mov_b32_e32 v47, v42
	v_pk_mul_f32 v[46:47], v[0:1], v[46:47] op_sel_hi:[0,1]
	v_pk_fma_f32 v[42:43], v[84:85], v[42:43], v[46:47] op_sel_hi:[0,1,1]
	s_waitcnt lgkmcnt(0)
	v_pk_add_f32 v[42:43], v[44:45], v[42:43]
	ds_write2st64_b32 v87, v42, v43 offset0:14 offset1:15
	ds_read_b64 v[44:45], v90 offset:8192
	v_xor_b32_e32 v46, 0x80000000, v43
	v_mov_b32_e32 v47, v42
	v_pk_mul_f32 v[46:47], v[0:1], v[46:47] op_sel_hi:[0,1]
	v_pk_fma_f32 v[42:43], v[84:85], v[42:43], v[46:47] op_sel_hi:[0,1,1]
	s_waitcnt lgkmcnt(0)
	v_pk_add_f32 v[42:43], v[44:45], v[42:43]
	ds_write2st64_b32 v100, v42, v43 offset0:16 offset1:17
	ds_read_b64 v[44:45], v90 offset:8704
	v_xor_b32_e32 v46, 0x80000000, v43
	v_mov_b32_e32 v47, v42
	v_pk_mul_f32 v[46:47], v[0:1], v[46:47] op_sel_hi:[0,1]
	v_pk_fma_f32 v[42:43], v[84:85], v[42:43], v[46:47] op_sel_hi:[0,1,1]
	s_waitcnt lgkmcnt(0)
	v_pk_add_f32 v[42:43], v[44:45], v[42:43]
	ds_write2st64_b32 v101, v42, v43 offset0:18 offset1:19
	ds_read_b64 v[44:45], v90 offset:9216
	v_xor_b32_e32 v46, 0x80000000, v43
	v_mov_b32_e32 v47, v42
	v_pk_mul_f32 v[46:47], v[0:1], v[46:47] op_sel_hi:[0,1]
	v_pk_fma_f32 v[42:43], v[84:85], v[42:43], v[46:47] op_sel_hi:[0,1,1]
	s_waitcnt lgkmcnt(0)
	v_pk_add_f32 v[42:43], v[44:45], v[42:43]
	ds_write2st64_b32 v102, v42, v43 offset0:20 offset1:21
	ds_read_b64 v[44:45], v90 offset:9728
	v_xor_b32_e32 v46, 0x80000000, v43
	v_mov_b32_e32 v47, v42
	v_pk_mul_f32 v[46:47], v[0:1], v[46:47] op_sel_hi:[0,1]
	v_pk_fma_f32 v[42:43], v[84:85], v[42:43], v[46:47] op_sel_hi:[0,1,1]
	s_waitcnt lgkmcnt(0)
; __device__ __forceinline__ float bf2f(bf16_t v) { return __uint_as_float(((unsigned)v) << 16); }
; __device__ __forceinline__ bf16_t f2bf(float f) { unsigned u = __float_as_uint(f); u += 0x7FFFu + ((u >> 16) & 1u); return (bf16_t)(u >> 16); }
; __device__ __forceinline__ void s5_pass2_item(PP p, unsigned char* shm, int item, int l) {
;     ...
;         for (int t = 0; t < 16; ++t) { s5_rec(q, *(const f32x2*)(buL + (t * 64 + lane) * 2), x); xs[t * 132 + lane] = x.x; xs[t * 132 + 64 + lane] = x.y; }
;         __syncthreads();
;         f32x4 y0 = (f32x4){0.f, 0.f, 0.f, 0.f}, y1 = y0;
;         const f32x4* xrow = (const f32x4*)(xs + cc * 132 + quad * 32);
; #pragma unroll
;         for (int i = 0; i < 8; ++i) { const f32x4 xv = xrow[i];
;             y0 = __builtin_amdgcn_mfma_f32_16x16x4f32(xv[0], cmr[4 * i + 0], y0, 0, 0, 0);
;             y1 = __builtin_amdgcn_mfma_f32_16x16x4f32(xv[1], cmr[4 * i + 1], y1, 0, 0, 0);
;             y0 = __builtin_amdgcn_mfma_f32_16x16x4f32(xv[2], cmr[4 * i + 2], y0, 0, 0, 0);
;             y1 = __builtin_amdgcn_mfma_f32_16x16x4f32(xv[3], cmr[4 * i + 3], y1, 0, 0, 0); }
;         const f32x4 y = y0 + y1;
; #pragma unroll
;         for (int r = 0; r < 4; ++r) { const int tl = sc * 16 + quad * 4 + r;
;             const float v = y[r] + dsk * bf2f(proj[PJ_UA + (row0 + tl) * 512 + g * 16 + cc]);
;             const float z = 0.7978845608028654f * (v + 0.044715f * v * v * v);
;             const float th = 1.0f - 2.0f / (__expf(2.0f * z) + 1.0f);
;             Gout[(row0 + tl) * 512 + g * 16 + cc] = f2bf(0.5f * v * (1.0f + th)); }
	v_pk_add_f32 v[42:43], v[44:45], v[42:43]
	ds_write2st64_b32 v103, v42, v43 offset0:22 offset1:23
	ds_read_b64 v[44:45], v90 offset:10240
	v_xor_b32_e32 v46, 0x80000000, v43
	v_mov_b32_e32 v47, v42
	v_pk_mul_f32 v[46:47], v[0:1], v[46:47] op_sel_hi:[0,1]
	v_pk_fma_f32 v[42:43], v[84:85], v[42:43], v[46:47] op_sel_hi:[0,1,1]
	s_waitcnt lgkmcnt(0)
	v_pk_add_f32 v[42:43], v[44:45], v[42:43]
	ds_write2st64_b32 v104, v42, v43 offset0:24 offset1:25
	ds_read_b64 v[44:45], v90 offset:10752
	v_xor_b32_e32 v46, 0x80000000, v43
	v_mov_b32_e32 v47, v42
	v_pk_mul_f32 v[46:47], v[0:1], v[46:47] op_sel_hi:[0,1]
	v_pk_fma_f32 v[42:43], v[84:85], v[42:43], v[46:47] op_sel_hi:[0,1,1]
	s_waitcnt lgkmcnt(0)
	v_pk_add_f32 v[42:43], v[44:45], v[42:43]
	ds_write2st64_b32 v105, v42, v43 offset0:26 offset1:27
	ds_read_b64 v[44:45], v90 offset:11264
	v_xor_b32_e32 v46, 0x80000000, v43
	v_mov_b32_e32 v47, v42
	v_pk_mul_f32 v[46:47], v[0:1], v[46:47] op_sel_hi:[0,1]
	v_pk_fma_f32 v[42:43], v[84:85], v[42:43], v[46:47] op_sel_hi:[0,1,1]
	s_waitcnt lgkmcnt(0)
	v_pk_add_f32 v[42:43], v[44:45], v[42:43]
	ds_write2st64_b32 v106, v42, v43 offset0:28 offset1:29
	ds_read_b64 v[44:45], v90 offset:11776
	v_xor_b32_e32 v46, 0x80000000, v43
	v_mov_b32_e32 v47, v42
	v_pk_mul_f32 v[46:47], v[0:1], v[46:47] op_sel_hi:[0,1]
	v_pk_fma_f32 v[42:43], v[84:85], v[42:43], v[46:47] op_sel_hi:[0,1,1]
	s_waitcnt lgkmcnt(0)
	v_pk_add_f32 v[46:47], v[44:45], v[42:43]
	ds_write2st64_b32 v107, v46, v47 offset0:30 offset1:31
	s_waitcnt lgkmcnt(0)
	s_barrier
	v_or_b32_e32 v216, 16, v82
	v_mov_b32_e32 v217, v83
	v_lshlrev_b64 v[216:217], 9, v[216:217]
	v_lshl_add_u64 v[216:217], v[216:217], 0, v[50:51]
	v_lshlrev_b64 v[216:217], 1, v[216:217]
	v_lshl_add_u64 v[216:217], s[8:9], 0, v[216:217]
	global_load_ushort v204, v[216:217], off
	global_load_ushort v205, v[216:217], off offset:1024
	global_load_ushort v206, v[216:217], off offset:2048
	global_load_ushort v207, v[216:217], off offset:3072
	ds_read_b128 v[42:45], v89
	ds_read_b128 v[110:113], v89 offset:16
	ds_read_b128 v[114:117], v89 offset:32
	ds_read_b128 v[118:121], v89 offset:48
	s_waitcnt lgkmcnt(3)
	v_mfma_f32_16x16x4_f32 v[122:125], v42, v97, 0
	v_or_b32_e32 v48, 16, v82
	v_mov_b32_e32 v49, v83
	v_lshlrev_b64 v[48:49], 9, v[48:49]
	v_lshl_add_u64 v[48:49], v[48:49], 0, v[50:51]
	v_lshlrev_b64 v[48:49], 1, v[48:49]
	v_lshl_add_u64 v[52:53], s[8:9], 0, v[48:49]
	v_mfma_f32_16x16x4_f32 v[126:129], v43, v96, 0
	v_lshl_add_u64 v[48:49], s[28:29], 0, v[48:49]
	s_waitcnt vmcnt(3)
	v_lshlrev_b32_e32 v52, 16, v204
	v_mfma_f32_16x16x4_f32 v[122:125], v44, v95, v[122:125]
	v_mfma_f32_16x16x4_f32 v[42:45], v45, v94, v[126:129]
	s_waitcnt lgkmcnt(2)
	v_mfma_f32_16x16x4_f32 v[122:125], v110, v93, v[122:125]
	v_mfma_f32_16x16x4_f32 v[42:45], v111, v92, v[42:45]
	v_mfma_f32_16x16x4_f32 v[122:125], v112, v91, v[122:125]
	v_mfma_f32_16x16x4_f32 v[42:45], v113, v88, v[42:45]
	s_waitcnt lgkmcnt(1)
	v_mfma_f32_16x16x4_f32 v[110:113], v114, v85, v[122:125]
	v_mfma_f32_16x16x4_f32 v[42:45], v115, v55, v[42:45]
	v_mfma_f32_16x16x4_f32 v[110:113], v116, v56, v[110:113]
	v_mfma_f32_16x16x4_f32 v[42:45], v117, v57, v[42:45]
	ds_read_b128 v[114:117], v89 offset:64
	s_waitcnt lgkmcnt(1)
	v_mfma_f32_16x16x4_f32 v[110:113], v118, v58, v[110:113]
	v_mfma_f32_16x16x4_f32 v[42:45], v119, v59, v[42:45]
	v_mfma_f32_16x16x4_f32 v[110:113], v120, v60, v[110:113]
	v_mfma_f32_16x16x4_f32 v[42:45], v121, v61, v[42:45]
	s_waitcnt lgkmcnt(0)
	v_mfma_f32_16x16x4_f32 v[110:113], v114, v62, v[110:113]
	v_mfma_f32_16x16x4_f32 v[42:45], v115, v63, v[42:45]
	v_mfma_f32_16x16x4_f32 v[110:113], v116, v64, v[110:113]
	v_mfma_f32_16x16x4_f32 v[42:45], v117, v65, v[42:45]
	ds_read_b128 v[114:117], v89 offset:80
	s_waitcnt lgkmcnt(0)
	v_mfma_f32_16x16x4_f32 v[110:113], v114, v66, v[110:113]
	v_mfma_f32_16x16x4_f32 v[42:45], v115, v67, v[42:45]
	v_mfma_f32_16x16x4_f32 v[110:113], v116, v68, v[110:113]
	v_mfma_f32_16x16x4_f32 v[42:45], v117, v69, v[42:45]
	ds_read_b128 v[114:117], v89 offset:96
	s_waitcnt lgkmcnt(0)
	v_mfma_f32_16x16x4_f32 v[110:113], v114, v70, v[110:113]
	v_mfma_f32_16x16x4_f32 v[42:45], v115, v71, v[42:45]
	v_mfma_f32_16x16x4_f32 v[110:113], v116, v72, v[110:113]
	v_mfma_f32_16x16x4_f32 v[42:45], v117, v73, v[42:45]
	ds_read_b128 v[114:117], v89 offset:112
	s_waitcnt lgkmcnt(0)
	v_mfma_f32_16x16x4_f32 v[110:113], v114, v74, v[110:113]
	v_mfma_f32_16x16x4_f32 v[42:45], v115, v75, v[42:45]
	v_mfma_f32_16x16x4_f32 v[110:113], v116, v76, v[110:113]
	v_mfma_f32_16x16x4_f32 v[42:45], v117, v77, v[42:45]
	v_mfma_f32_16x16x32_bf16 v[114:117], v[38:41], v[30:33], 0
	s_nop 8
	v_add_f32_e64 v42, v110, v42
	v_add_f32_e64 v43, v111, v43
	v_pk_add_f32 v[44:45], v[112:113], v[44:45]
	v_fma_f32 v42, v54, v52, v42
	v_mul_f32_e32 v52, 0x3d372713, v42
	v_mul_f32_e32 v52, v42, v52
	v_fma_f32 v52, v42, v52, v42
	v_mul_f32_e32 v52, 0x3f4c422a, v52
	v_add_f32_e32 v52, v52, v52
	v_mul_f32_e32 v52, 0x3fb8aa3b, v52
	v_exp_f32_e32 v52, v52
	v_mul_f32_e32 v42, 0.5, v42
	v_mov_b32_e32 v119, v114
	v_mfma_f32_16x16x32_bf16 v[30:33], v[2:5], v[30:33], 0
	v_add_f32_e32 v52, 1.0, v52
	v_div_scale_f32 v53, s[2:3], v52, v52, 2.0
	v_rcp_f32_e32 v109, v53
	s_nop 0
	v_fma_f32 v110, -v53, v109, 1.0
	v_fmac_f32_e32 v109, v110, v109
	v_div_scale_f32 v110, vcc, 2.0, v52, 2.0
	v_mul_f32_e32 v111, v110, v109
	v_fma_f32 v112, -v53, v111, v110
	v_fmac_f32_e32 v111, v112, v109
	v_fma_f32 v53, -v53, v111, v110
	v_div_fmas_f32 v53, v53, v109, v111
	v_div_fixup_f32 v52, v53, v52, 2.0
	v_sub_f32_e32 v52, 1.0, v52
	v_add_f32_e32 v52, 1.0, v52
	v_mul_f32_e32 v42, v42, v52
	v_bfe_u32 v52, v42, 16, 1
	v_add3_u32 v42, v42, v52, s31
	global_store_short_d16_hi v[48:49], v42, off
	v_or_b32_e32 v48, 17, v82
	v_mov_b32_e32 v49, v83
	v_lshlrev_b64 v[48:49], 9, v[48:49]
	v_lshl_add_u64 v[48:49], v[48:49], 0, v[50:51]
	v_lshlrev_b64 v[48:49], 1, v[48:49]
	v_lshl_add_u64 v[52:53], s[8:9], 0, v[48:49]
	s_waitcnt vmcnt(3)
; __device__ __forceinline__ float bf2f(bf16_t v) { return __uint_as_float(((unsigned)v) << 16); }
; __device__ __forceinline__ bf16_t f2bf(float f) { unsigned u = __float_as_uint(f); u += 0x7FFFu + ((u >> 16) & 1u); return (bf16_t)(u >> 16); }
; __device__ __forceinline__ void s5_bu16(const S5Frag& f, const bf16x8 uf, float* buL, int lane) {
;     const int jj = lane & 15, quad = lane >> 4;
; #pragma unroll
;     for (int nt = 0; nt < 4; ++nt) {
;         const f32x4 z = (f32x4){0.f, 0.f, 0.f, 0.f};
;         const f32x4 dre = __builtin_amdgcn_mfma_f32_16x16x32_bf16(uf, f.bfr[nt], z, 0, 0, 0);
;         const f32x4 dim = __builtin_amdgcn_mfma_f32_16x16x32_bf16(uf, f.bfr[nt + 4], z, 0, 0, 0);
; #pragma unroll
;         for (int r = 0; r < 4; ++r) *(f32x2*)(buL + ((4 * quad + r) * 64 + 16 * nt + jj) * 2) = (f32x2){dre[r], dim[r]};
;     }
; __device__ __forceinline__ void s5_pass2_item(PP p, unsigned char* shm, int item, int l) {
;     ...
;         const f32x4 y = y0 + y1;
; #pragma unroll
;         for (int r = 0; r < 4; ++r) { const int tl = sc * 16 + quad * 4 + r;
;             const float v = y[r] + dsk * bf2f(proj[PJ_UA + (row0 + tl) * 512 + g * 16 + cc]);
;             const float z = 0.7978845608028654f * (v + 0.044715f * v * v * v);
;             const float th = 1.0f - 2.0f / (__expf(2.0f * z) + 1.0f);
;             Gout[(row0 + tl) * 512 + g * 16 + cc] = f2bf(0.5f * v * (1.0f + th)); }
	v_lshlrev_b32_e32 v42, 16, v205
	v_fmac_f32_e32 v43, v54, v42
	v_mul_f32_e32 v42, 0x3d372713, v43
	v_mul_f32_e32 v42, v43, v42
	v_fma_f32 v42, v43, v42, v43
	v_mul_f32_e32 v42, 0x3f4c422a, v42
	v_add_f32_e32 v42, v42, v42
	v_mul_f32_e32 v42, 0x3fb8aa3b, v42
	v_exp_f32_e32 v42, v42
	v_mul_f32_e32 v43, 0.5, v43
	v_add_f32_e32 v42, 1.0, v42
	v_div_scale_f32 v52, s[2:3], v42, v42, 2.0
	v_rcp_f32_e32 v53, v52
	s_nop 0
	v_fma_f32 v109, -v52, v53, 1.0
	v_fmac_f32_e32 v53, v109, v53
	v_div_scale_f32 v109, vcc, 2.0, v42, 2.0
	v_mul_f32_e32 v110, v109, v53
	v_fma_f32 v111, -v52, v110, v109
	v_fmac_f32_e32 v110, v111, v53
	v_fma_f32 v52, -v52, v110, v109
	v_div_fmas_f32 v52, v52, v53, v110
	v_div_fixup_f32 v42, v52, v42, 2.0
	v_sub_f32_e32 v42, 1.0, v42
	v_add_f32_e32 v42, 1.0, v42
	v_mul_f32_e32 v42, v43, v42
	v_bfe_u32 v43, v42, 16, 1
	v_add3_u32 v52, v42, v43, s31
	v_lshl_add_u64 v[42:43], s[28:29], 0, v[48:49]
	global_store_short_d16_hi v[42:43], v52, off
	v_or_b32_e32 v42, 18, v82
	v_mov_b32_e32 v43, v83
	v_lshlrev_b64 v[42:43], 9, v[42:43]
	v_lshl_add_u64 v[42:43], v[42:43], 0, v[50:51]
	v_lshlrev_b64 v[42:43], 1, v[42:43]
	v_lshl_add_u64 v[48:49], s[8:9], 0, v[42:43]
	v_lshl_add_u64 v[42:43], s[28:29], 0, v[42:43]
	s_waitcnt vmcnt(3)
	v_lshlrev_b32_e32 v48, 16, v206
	v_fma_f32 v44, v54, v48, v44
	v_mul_f32_e32 v48, 0x3d372713, v44
	v_mul_f32_e32 v48, v44, v48
	v_fma_f32 v48, v44, v48, v44
	v_mul_f32_e32 v48, 0x3f4c422a, v48
	v_add_f32_e32 v48, v48, v48
	v_mul_f32_e32 v48, 0x3fb8aa3b, v48
	v_exp_f32_e32 v48, v48
	v_mul_f32_e32 v44, 0.5, v44
	v_add_f32_e32 v48, 1.0, v48
	v_div_scale_f32 v49, s[2:3], v48, v48, 2.0
	v_rcp_f32_e32 v52, v49
	s_nop 0
	v_fma_f32 v53, -v49, v52, 1.0
	v_fmac_f32_e32 v52, v53, v52
	v_div_scale_f32 v53, vcc, 2.0, v48, 2.0
	v_mul_f32_e32 v109, v53, v52
	v_fma_f32 v110, -v49, v109, v53
	v_fmac_f32_e32 v109, v110, v52
	v_fma_f32 v49, -v49, v109, v53
	v_div_fmas_f32 v49, v49, v52, v109
	v_div_fixup_f32 v48, v49, v48, 2.0
	v_sub_f32_e32 v48, 1.0, v48
	v_add_f32_e32 v48, 1.0, v48
	v_mul_f32_e32 v44, v44, v48
	v_bfe_u32 v48, v44, 16, 1
	v_add3_u32 v44, v44, v48, s31
	global_store_short_d16_hi v[42:43], v44, off
	v_or_b32_e32 v42, 19, v82
	v_mov_b32_e32 v43, v83
	v_lshlrev_b64 v[42:43], 9, v[42:43]
	v_lshl_add_u64 v[42:43], v[42:43], 0, v[50:51]
	v_lshlrev_b64 v[42:43], 1, v[42:43]
	v_lshl_add_u64 v[48:49], s[8:9], 0, v[42:43]
	v_lshl_add_u64 v[42:43], s[28:29], 0, v[42:43]
	v_mfma_f32_16x16x32_bf16 v[110:113], v[38:41], v[26:29], 0
	s_waitcnt vmcnt(3)
	v_lshlrev_b32_e32 v44, 16, v207
	v_fmac_f32_e32 v45, v54, v44
	v_mul_f32_e32 v44, 0x3d372713, v45
	v_mul_f32_e32 v44, v45, v44
	v_fma_f32 v44, v45, v44, v45
	v_mul_f32_e32 v44, 0x3f4c422a, v44
	v_add_f32_e32 v44, v44, v44
	v_mul_f32_e32 v44, 0x3fb8aa3b, v44
	v_exp_f32_e32 v44, v44
	v_mul_f32_e32 v45, 0.5, v45
	v_add_f32_e32 v44, 1.0, v44
	v_div_scale_f32 v48, s[2:3], v44, v44, 2.0
	v_rcp_f32_e32 v49, v48
	s_nop 0
	v_fma_f32 v52, -v48, v49, 1.0
	v_fmac_f32_e32 v49, v52, v49
	v_div_scale_f32 v52, vcc, 2.0, v44, 2.0
	v_mul_f32_e32 v53, v52, v49
	v_fma_f32 v109, -v48, v53, v52
	v_fmac_f32_e32 v53, v109, v49
	v_fma_f32 v48, -v48, v53, v52
	v_div_fmas_f32 v48, v48, v49, v53
	v_div_fixup_f32 v44, v48, v44, 2.0
	v_sub_f32_e32 v44, 1.0, v44
	v_add_f32_e32 v44, 1.0, v44
	v_mul_f32_e32 v44, v45, v44
	v_bfe_u32 v45, v44, 16, 1
	v_add3_u32 v44, v44, v45, s31
	global_store_short_d16_hi v[42:43], v44, off
	v_mfma_f32_16x16x32_bf16 v[42:45], v[38:41], v[34:37], 0
	v_mov_b32_e32 v48, v110
	v_mov_b32_e32 v52, v112
	s_barrier
	s_nop 4
	v_mov_b32_e32 v49, v42
	v_mov_b32_e32 v42, v111
	v_mov_b32_e32 v53, v44
	v_mov_b32_e32 v44, v113
	v_mfma_f32_16x16x32_bf16 v[110:113], v[38:41], v[22:25], 0
	v_mfma_f32_16x16x32_bf16 v[22:25], v[2:5], v[22:25], 0
	s_nop 6
	v_mov_b32_e32 v118, v110
	ds_write2_b64 v108, v[48:49], v[118:119] offset1:16
	v_mov_b32_e32 v114, v111
	v_mov_b32_e32 v48, v112
	v_mov_b32_e32 v49, v116
	v_mov_b32_e32 v116, v113
	v_mfma_f32_16x16x32_bf16 v[110:113], v[38:41], v[18:21], 0
	ds_write2_b64 v108, v[52:53], v[48:49] offset0:128 offset1:144
	v_mfma_f32_16x16x32_bf16 v[118:121], v[38:41], v[14:17], 0
	v_mfma_f32_16x16x32_bf16 v[18:21], v[2:5], v[18:21], 0
	s_nop 4
	v_mov_b32_e32 v48, v110
	s_nop 0
	v_mov_b32_e32 v49, v118
	ds_write2_b64 v108, v[48:49], v[42:43] offset0:32 offset1:64
	v_mov_b32_e32 v42, v112
	v_mov_b32_e32 v43, v120
	ds_write2_b64 v108, v[42:43], v[44:45] offset0:160 offset1:192
	v_mfma_f32_16x16x32_bf16 v[42:45], v[38:41], v[10:13], 0
	v_mov_b32_e32 v118, v111
	v_mov_b32_e32 v120, v113
	ds_write2_b64 v108, v[114:115], v[118:119] offset0:80 offset1:96
	v_mfma_f32_16x16x32_bf16 v[38:41], v[38:41], v[6:9], 0
	ds_write2_b64 v108, v[116:117], v[120:121] offset0:208 offset1:224
	s_nop 2
	v_mov_b32_e32 v48, v42
	v_mfma_f32_16x16x32_bf16 v[14:17], v[2:5], v[14:17], 0
	v_mfma_f32_16x16x32_bf16 v[10:13], v[2:5], v[10:13], 0
	s_nop 0
	v_mov_b32_e32 v49, v38
	v_mov_b32_e32 v38, v43
	ds_write2st64_b64 v99, v[48:49], v[38:39] offset0:8 offset1:9
	v_mov_b32_e32 v38, v44
	v_mov_b32_e32 v39, v40
	v_mov_b32_e32 v40, v45
	ds_write2st64_b64 v99, v[38:39], v[40:41] offset0:10 offset1:11
	s_waitcnt lgkmcnt(0)
	s_barrier
; __device__ __forceinline__ void s5_pass2_item(PP p, unsigned char* shm, int item, int l) {
;     ...
; #pragma unroll
;         for (int t = 0; t < 16; ++t) { s5_rec(q, *(const f32x2*)(buL + (t * 64 + lane) * 2), x); xs[t * 132 + lane] = x.x; xs[t * 132 + 64 + lane] = x.y; }
;         __syncthreads();
	ds_read_b64 v[38:39], v90 offset:4096
	v_xor_b32_e32 v40, 0x80000000, v47
	v_mov_b32_e32 v41, v46
	v_pk_mul_f32 v[40:41], v[0:1], v[40:41] op_sel_hi:[0,1]
	v_pk_fma_f32 v[40:41], v[84:85], v[46:47], v[40:41] op_sel_hi:[0,1,1]
	s_waitcnt lgkmcnt(0)
	v_pk_add_f32 v[38:39], v[40:41], v[38:39]
	ds_write2st64_b32 v98, v38, v39 offset1:1
	ds_read_b64 v[40:41], v90 offset:4608
	v_xor_b32_e32 v42, 0x80000000, v39
	v_mov_b32_e32 v43, v38
	v_pk_mul_f32 v[42:43], v[0:1], v[42:43] op_sel_hi:[0,1]
	v_pk_fma_f32 v[38:39], v[84:85], v[38:39], v[42:43] op_sel_hi:[0,1,1]
	s_waitcnt lgkmcnt(0)
	v_pk_add_f32 v[38:39], v[40:41], v[38:39]
	ds_write2_b32 v98, v38, v39 offset0:132 offset1:196
	ds_read_b64 v[40:41], v90 offset:5120
	v_xor_b32_e32 v42, 0x80000000, v39
	v_mov_b32_e32 v43, v38
	v_pk_mul_f32 v[42:43], v[0:1], v[42:43] op_sel_hi:[0,1]
	v_pk_fma_f32 v[38:39], v[84:85], v[38:39], v[42:43] op_sel_hi:[0,1,1]
	s_waitcnt lgkmcnt(0)
	v_pk_add_f32 v[38:39], v[40:41], v[38:39]
	ds_write2st64_b32 v78, v38, v39 offset0:4 offset1:5
	ds_read_b64 v[40:41], v90 offset:5632
	v_xor_b32_e32 v42, 0x80000000, v39
	v_mov_b32_e32 v43, v38
	v_pk_mul_f32 v[42:43], v[0:1], v[42:43] op_sel_hi:[0,1]
	v_pk_fma_f32 v[38:39], v[84:85], v[38:39], v[42:43] op_sel_hi:[0,1,1]
	s_waitcnt lgkmcnt(0)
	v_pk_add_f32 v[38:39], v[40:41], v[38:39]
	ds_write2st64_b32 v79, v38, v39 offset0:6 offset1:7
	ds_read_b64 v[40:41], v90 offset:6144
	v_xor_b32_e32 v42, 0x80000000, v39
	v_mov_b32_e32 v43, v38
	v_pk_mul_f32 v[42:43], v[0:1], v[42:43] op_sel_hi:[0,1]
	v_pk_fma_f32 v[38:39], v[84:85], v[38:39], v[42:43] op_sel_hi:[0,1,1]
	s_waitcnt lgkmcnt(0)
	v_pk_add_f32 v[38:39], v[40:41], v[38:39]
	ds_write2st64_b32 v80, v38, v39 offset0:8 offset1:9
	ds_read_b64 v[40:41], v90 offset:6656
	v_xor_b32_e32 v42, 0x80000000, v39
	v_mov_b32_e32 v43, v38
	v_pk_mul_f32 v[42:43], v[0:1], v[42:43] op_sel_hi:[0,1]
	v_pk_fma_f32 v[38:39], v[84:85], v[38:39], v[42:43] op_sel_hi:[0,1,1]
	s_waitcnt lgkmcnt(0)
	v_pk_add_f32 v[38:39], v[40:41], v[38:39]
	ds_write2st64_b32 v81, v38, v39 offset0:10 offset1:11
	ds_read_b64 v[40:41], v90 offset:7168
	v_xor_b32_e32 v42, 0x80000000, v39
	v_mov_b32_e32 v43, v38
	v_pk_mul_f32 v[42:43], v[0:1], v[42:43] op_sel_hi:[0,1]
	v_pk_fma_f32 v[38:39], v[84:85], v[38:39], v[42:43] op_sel_hi:[0,1,1]
	s_waitcnt lgkmcnt(0)
	v_pk_add_f32 v[38:39], v[40:41], v[38:39]
	ds_write2st64_b32 v86, v38, v39 offset0:12 offset1:13
	ds_read_b64 v[40:41], v90 offset:7680
	v_xor_b32_e32 v42, 0x80000000, v39
	v_mov_b32_e32 v43, v38
	v_pk_mul_f32 v[42:43], v[0:1], v[42:43] op_sel_hi:[0,1]
	v_pk_fma_f32 v[38:39], v[84:85], v[38:39], v[42:43] op_sel_hi:[0,1,1]
	s_waitcnt lgkmcnt(0)
	v_pk_add_f32 v[38:39], v[40:41], v[38:39]
	ds_write2st64_b32 v87, v38, v39 offset0:14 offset1:15
	ds_read_b64 v[40:41], v90 offset:8192
	v_xor_b32_e32 v42, 0x80000000, v39
	v_mov_b32_e32 v43, v38
	v_pk_mul_f32 v[42:43], v[0:1], v[42:43] op_sel_hi:[0,1]
	v_pk_fma_f32 v[38:39], v[84:85], v[38:39], v[42:43] op_sel_hi:[0,1,1]
	s_waitcnt lgkmcnt(0)
	v_pk_add_f32 v[38:39], v[40:41], v[38:39]
	ds_write2st64_b32 v100, v38, v39 offset0:16 offset1:17
	ds_read_b64 v[40:41], v90 offset:8704
	v_xor_b32_e32 v42, 0x80000000, v39
	v_mov_b32_e32 v43, v38
	v_pk_mul_f32 v[42:43], v[0:1], v[42:43] op_sel_hi:[0,1]
	v_pk_fma_f32 v[38:39], v[84:85], v[38:39], v[42:43] op_sel_hi:[0,1,1]
	s_waitcnt lgkmcnt(0)
	v_pk_add_f32 v[38:39], v[40:41], v[38:39]
	ds_write2st64_b32 v101, v38, v39 offset0:18 offset1:19
	ds_read_b64 v[40:41], v90 offset:9216
	v_xor_b32_e32 v42, 0x80000000, v39
	v_mov_b32_e32 v43, v38
	v_pk_mul_f32 v[42:43], v[0:1], v[42:43] op_sel_hi:[0,1]
	v_pk_fma_f32 v[38:39], v[84:85], v[38:39], v[42:43] op_sel_hi:[0,1,1]
	s_waitcnt lgkmcnt(0)
	v_pk_add_f32 v[38:39], v[40:41], v[38:39]
	ds_write2st64_b32 v102, v38, v39 offset0:20 offset1:21
	ds_read_b64 v[40:41], v90 offset:9728
	v_xor_b32_e32 v42, 0x80000000, v39
	v_mov_b32_e32 v43, v38
	v_pk_mul_f32 v[42:43], v[0:1], v[42:43] op_sel_hi:[0,1]
	v_pk_fma_f32 v[38:39], v[84:85], v[38:39], v[42:43] op_sel_hi:[0,1,1]
	s_waitcnt lgkmcnt(0)
	v_pk_add_f32 v[38:39], v[40:41], v[38:39]
	ds_write2st64_b32 v103, v38, v39 offset0:22 offset1:23
	ds_read_b64 v[40:41], v90 offset:10240
	v_xor_b32_e32 v42, 0x80000000, v39
	v_mov_b32_e32 v43, v38
	v_pk_mul_f32 v[42:43], v[0:1], v[42:43] op_sel_hi:[0,1]
	v_pk_fma_f32 v[38:39], v[84:85], v[38:39], v[42:43] op_sel_hi:[0,1,1]
	s_waitcnt lgkmcnt(0)
	v_pk_add_f32 v[38:39], v[40:41], v[38:39]
	ds_write2st64_b32 v104, v38, v39 offset0:24 offset1:25
	ds_read_b64 v[40:41], v90 offset:10752
	v_xor_b32_e32 v42, 0x80000000, v39
	v_mov_b32_e32 v43, v38
	v_pk_mul_f32 v[42:43], v[0:1], v[42:43] op_sel_hi:[0,1]
	v_pk_fma_f32 v[38:39], v[84:85], v[38:39], v[42:43] op_sel_hi:[0,1,1]
	s_waitcnt lgkmcnt(0)
	v_pk_add_f32 v[38:39], v[40:41], v[38:39]
	ds_write2st64_b32 v105, v38, v39 offset0:26 offset1:27
	ds_read_b64 v[40:41], v90 offset:11264
	v_xor_b32_e32 v42, 0x80000000, v39
	v_mov_b32_e32 v43, v38
	v_pk_mul_f32 v[42:43], v[0:1], v[42:43] op_sel_hi:[0,1]
	v_pk_fma_f32 v[38:39], v[84:85], v[38:39], v[42:43] op_sel_hi:[0,1,1]
	s_waitcnt lgkmcnt(0)
	v_pk_add_f32 v[38:39], v[40:41], v[38:39]
	ds_write2st64_b32 v106, v38, v39 offset0:28 offset1:29
	ds_read_b64 v[40:41], v90 offset:11776
	v_xor_b32_e32 v42, 0x80000000, v39
	v_mov_b32_e32 v43, v38
	v_pk_mul_f32 v[42:43], v[0:1], v[42:43] op_sel_hi:[0,1]
	v_pk_fma_f32 v[38:39], v[84:85], v[38:39], v[42:43] op_sel_hi:[0,1,1]
	s_waitcnt lgkmcnt(0)
	v_pk_add_f32 v[38:39], v[40:41], v[38:39]
	ds_write2st64_b32 v107, v38, v39 offset0:30 offset1:31
	s_waitcnt lgkmcnt(0)
	s_barrier
; __device__ __forceinline__ float bf2f(bf16_t v) { return __uint_as_float(((unsigned)v) << 16); }
; __device__ __forceinline__ bf16_t f2bf(float f) { unsigned u = __float_as_uint(f); u += 0x7FFFu + ((u >> 16) & 1u); return (bf16_t)(u >> 16); }
; __device__ __forceinline__ void s5_pass2_item(PP p, unsigned char* shm, int item, int l) {
;     ...
;         f32x4 y0 = (f32x4){0.f, 0.f, 0.f, 0.f}, y1 = y0;
;         const f32x4* xrow = (const f32x4*)(xs + cc * 132 + quad * 32);
; #pragma unroll
;         for (int i = 0; i < 8; ++i) { const f32x4 xv = xrow[i];
;             y0 = __builtin_amdgcn_mfma_f32_16x16x4f32(xv[0], cmr[4 * i + 0], y0, 0, 0, 0);
;             y1 = __builtin_amdgcn_mfma_f32_16x16x4f32(xv[1], cmr[4 * i + 1], y1, 0, 0, 0);
;             y0 = __builtin_amdgcn_mfma_f32_16x16x4f32(xv[2], cmr[4 * i + 2], y0, 0, 0, 0);
;             y1 = __builtin_amdgcn_mfma_f32_16x16x4f32(xv[3], cmr[4 * i + 3], y1, 0, 0, 0); }
;         const f32x4 y = y0 + y1;
; #pragma unroll
;         for (int r = 0; r < 4; ++r) { const int tl = sc * 16 + quad * 4 + r;
;             const float v = y[r] + dsk * bf2f(proj[PJ_UA + (row0 + tl) * 512 + g * 16 + cc]);
;             const float z = 0.7978845608028654f * (v + 0.044715f * v * v * v);
;             const float th = 1.0f - 2.0f / (__expf(2.0f * z) + 1.0f);
;             Gout[(row0 + tl) * 512 + g * 16 + cc] = f2bf(0.5f * v * (1.0f + th)); }
	v_or_b32_e32 v216, 32, v82
	v_mov_b32_e32 v217, v83
	v_lshlrev_b64 v[216:217], 9, v[216:217]
	v_lshl_add_u64 v[216:217], v[216:217], 0, v[50:51]
	v_lshlrev_b64 v[216:217], 1, v[216:217]
	v_lshl_add_u64 v[216:217], s[8:9], 0, v[216:217]
	global_load_ushort v208, v[216:217], off
	global_load_ushort v209, v[216:217], off offset:1024
	global_load_ushort v210, v[216:217], off offset:2048
	global_load_ushort v211, v[216:217], off offset:3072
	ds_read_b128 v[40:43], v89
	ds_read_b128 v[44:47], v89 offset:16
	ds_read_b128 v[110:113], v89 offset:32
	ds_read_b128 v[114:117], v89 offset:48
	s_waitcnt lgkmcnt(3)
	v_mfma_f32_16x16x4_f32 v[118:121], v40, v97, 0
	v_mfma_f32_16x16x4_f32 v[122:125], v41, v96, 0
	v_mfma_f32_16x16x4_f32 v[118:121], v42, v95, v[118:121]
	v_mfma_f32_16x16x4_f32 v[40:43], v43, v94, v[122:125]
	s_waitcnt lgkmcnt(2)
	v_mfma_f32_16x16x4_f32 v[118:121], v44, v93, v[118:121]
	v_mfma_f32_16x16x4_f32 v[40:43], v45, v92, v[40:43]
	v_mfma_f32_16x16x4_f32 v[118:121], v46, v91, v[118:121]
	v_mfma_f32_16x16x4_f32 v[40:43], v47, v88, v[40:43]
	s_waitcnt lgkmcnt(1)
	v_mfma_f32_16x16x4_f32 v[44:47], v110, v85, v[118:121]
	v_mfma_f32_16x16x4_f32 v[40:43], v111, v55, v[40:43]
	v_mfma_f32_16x16x4_f32 v[44:47], v112, v56, v[44:47]
	v_mfma_f32_16x16x4_f32 v[40:43], v113, v57, v[40:43]
	ds_read_b128 v[110:113], v89 offset:64
	s_waitcnt lgkmcnt(1)
	v_mfma_f32_16x16x4_f32 v[44:47], v114, v58, v[44:47]
	v_mfma_f32_16x16x4_f32 v[40:43], v115, v59, v[40:43]
	v_mfma_f32_16x16x4_f32 v[44:47], v116, v60, v[44:47]
	v_mfma_f32_16x16x4_f32 v[40:43], v117, v61, v[40:43]
	s_waitcnt lgkmcnt(0)
	v_mfma_f32_16x16x4_f32 v[44:47], v110, v62, v[44:47]
	v_mfma_f32_16x16x4_f32 v[40:43], v111, v63, v[40:43]
	v_mfma_f32_16x16x4_f32 v[44:47], v112, v64, v[44:47]
	v_mfma_f32_16x16x4_f32 v[40:43], v113, v65, v[40:43]
	ds_read_b128 v[110:113], v89 offset:80
	s_waitcnt lgkmcnt(0)
	v_mfma_f32_16x16x4_f32 v[44:47], v110, v66, v[44:47]
	v_mfma_f32_16x16x4_f32 v[40:43], v111, v67, v[40:43]
	v_mfma_f32_16x16x4_f32 v[44:47], v112, v68, v[44:47]
	v_mfma_f32_16x16x4_f32 v[40:43], v113, v69, v[40:43]
	ds_read_b128 v[110:113], v89 offset:96
	s_waitcnt lgkmcnt(0)
	v_mfma_f32_16x16x4_f32 v[44:47], v110, v70, v[44:47]
	v_mfma_f32_16x16x4_f32 v[40:43], v111, v71, v[40:43]
	v_mfma_f32_16x16x4_f32 v[44:47], v112, v72, v[44:47]
	v_mfma_f32_16x16x4_f32 v[40:43], v113, v73, v[40:43]
	ds_read_b128 v[110:113], v89 offset:112
	s_waitcnt lgkmcnt(0)
	v_mfma_f32_16x16x4_f32 v[44:47], v110, v74, v[44:47]
	v_mfma_f32_16x16x4_f32 v[40:43], v111, v75, v[40:43]
	v_mfma_f32_16x16x4_f32 v[44:47], v112, v76, v[44:47]
	v_mfma_f32_16x16x4_f32 v[40:43], v113, v77, v[40:43]
	s_nop 9
	v_pk_add_f32 v[40:41], v[44:45], v[40:41]
	v_or_b32_e32 v44, 32, v82
	v_mov_b32_e32 v45, v83
	v_lshlrev_b64 v[44:45], 9, v[44:45]
	v_lshl_add_u64 v[44:45], v[44:45], 0, v[50:51]
	v_lshlrev_b64 v[44:45], 1, v[44:45]
	v_pk_add_f32 v[42:43], v[46:47], v[42:43]
	v_lshl_add_u64 v[46:47], s[8:9], 0, v[44:45]
	v_lshl_add_u64 v[44:45], s[28:29], 0, v[44:45]
	s_waitcnt vmcnt(3)
	v_lshlrev_b32_e32 v46, 16, v208
	v_fma_f32 v40, v54, v46, v40
	v_mul_f32_e32 v46, 0x3d372713, v40
	v_mul_f32_e32 v46, v40, v46
	v_fma_f32 v46, v40, v46, v40
	v_mul_f32_e32 v46, 0x3f4c422a, v46
	v_add_f32_e32 v46, v46, v46
	v_mul_f32_e32 v46, 0x3fb8aa3b, v46
	v_exp_f32_e32 v46, v46
	v_mul_f32_e32 v40, 0.5, v40
	v_add_f32_e32 v46, 1.0, v46
	v_div_scale_f32 v47, s[2:3], v46, v46, 2.0
	v_rcp_f32_e32 v48, v47
	s_nop 0
	v_fma_f32 v49, -v47, v48, 1.0
	v_fmac_f32_e32 v48, v49, v48
	v_div_scale_f32 v49, vcc, 2.0, v46, 2.0
	v_mul_f32_e32 v52, v49, v48
	v_fma_f32 v53, -v47, v52, v49
	v_fmac_f32_e32 v52, v53, v48
	v_fma_f32 v47, -v47, v52, v49
	v_div_fmas_f32 v47, v47, v48, v52
	v_div_fixup_f32 v46, v47, v46, 2.0
	v_sub_f32_e32 v46, 1.0, v46
	v_add_f32_e32 v46, 1.0, v46
	v_mul_f32_e32 v40, v40, v46
	v_bfe_u32 v46, v40, 16, 1
	v_add3_u32 v40, v40, v46, s31
	global_store_short_d16_hi v[44:45], v40, off
	v_or_b32_e32 v44, 33, v82
	v_mov_b32_e32 v45, v83
	v_lshlrev_b64 v[44:45], 9, v[44:45]
	v_lshl_add_u64 v[44:45], v[44:45], 0, v[50:51]
	v_lshlrev_b64 v[44:45], 1, v[44:45]
	v_lshl_add_u64 v[46:47], s[8:9], 0, v[44:45]
	s_waitcnt vmcnt(3)
	v_lshlrev_b32_e32 v40, 16, v209
	v_fmac_f32_e32 v41, v54, v40
	v_mul_f32_e32 v40, 0x3d372713, v41
	v_mul_f32_e32 v40, v41, v40
	v_fma_f32 v40, v41, v40, v41
	v_mul_f32_e32 v40, 0x3f4c422a, v40
	v_add_f32_e32 v40, v40, v40
	v_mul_f32_e32 v40, 0x3fb8aa3b, v40
	v_exp_f32_e32 v40, v40
	v_mul_f32_e32 v41, 0.5, v41
	v_add_f32_e32 v40, 1.0, v40
	v_div_scale_f32 v46, s[2:3], v40, v40, 2.0
	v_rcp_f32_e32 v47, v46
	s_nop 0
	v_fma_f32 v48, -v46, v47, 1.0
	v_fmac_f32_e32 v47, v48, v47
	v_div_scale_f32 v48, vcc, 2.0, v40, 2.0
	v_mul_f32_e32 v49, v48, v47
	v_fma_f32 v52, -v46, v49, v48
	v_fmac_f32_e32 v49, v52, v47
	v_fma_f32 v46, -v46, v49, v48
	v_div_fmas_f32 v46, v46, v47, v49
	v_div_fixup_f32 v40, v46, v40, 2.0
	v_sub_f32_e32 v40, 1.0, v40
	v_add_f32_e32 v40, 1.0, v40
	v_mul_f32_e32 v40, v41, v40
	v_bfe_u32 v41, v40, 16, 1
	v_add3_u32 v46, v40, v41, s31
	v_lshl_add_u64 v[40:41], s[28:29], 0, v[44:45]
	global_store_short_d16_hi v[40:41], v46, off
	v_or_b32_e32 v40, 34, v82
	v_mov_b32_e32 v41, v83
	v_lshlrev_b64 v[40:41], 9, v[40:41]
	v_lshl_add_u64 v[40:41], v[40:41], 0, v[50:51]
	v_lshlrev_b64 v[40:41], 1, v[40:41]
	v_lshl_add_u64 v[44:45], s[8:9], 0, v[40:41]
	v_lshl_add_u64 v[40:41], s[28:29], 0, v[40:41]
	s_waitcnt vmcnt(3)
; __device__ __forceinline__ float bf2f(bf16_t v) { return __uint_as_float(((unsigned)v) << 16); }
; __device__ __forceinline__ bf16_t f2bf(float f) { unsigned u = __float_as_uint(f); u += 0x7FFFu + ((u >> 16) & 1u); return (bf16_t)(u >> 16); }
; __device__ __forceinline__ void s5_bu16(const S5Frag& f, const bf16x8 uf, float* buL, int lane) {
;     const int jj = lane & 15, quad = lane >> 4;
; #pragma unroll
;     for (int nt = 0; nt < 4; ++nt) {
;         const f32x4 z = (f32x4){0.f, 0.f, 0.f, 0.f};
;         const f32x4 dre = __builtin_amdgcn_mfma_f32_16x16x32_bf16(uf, f.bfr[nt], z, 0, 0, 0);
;         const f32x4 dim = __builtin_amdgcn_mfma_f32_16x16x32_bf16(uf, f.bfr[nt + 4], z, 0, 0, 0);
; #pragma unroll
;         for (int r = 0; r < 4; ++r) *(f32x2*)(buL + ((4 * quad + r) * 64 + 16 * nt + jj) * 2) = (f32x2){dre[r], dim[r]};
;     }
; }
; __device__ __forceinline__ void s5_pass2_item(PP p, unsigned char* shm, int item, int l) {
;     ...
;         const f32x4 y = y0 + y1;
; #pragma unroll
;         for (int r = 0; r < 4; ++r) { const int tl = sc * 16 + quad * 4 + r;
;             const float v = y[r] + dsk * bf2f(proj[PJ_UA + (row0 + tl) * 512 + g * 16 + cc]);
;             const float z = 0.7978845608028654f * (v + 0.044715f * v * v * v);
;             const float th = 1.0f - 2.0f / (__expf(2.0f * z) + 1.0f);
;             Gout[(row0 + tl) * 512 + g * 16 + cc] = f2bf(0.5f * v * (1.0f + th)); }
	v_lshlrev_b32_e32 v44, 16, v210
	v_fma_f32 v42, v54, v44, v42
	v_mul_f32_e32 v44, 0x3d372713, v42
	v_mul_f32_e32 v44, v42, v44
	v_fma_f32 v44, v42, v44, v42
	v_mul_f32_e32 v44, 0x3f4c422a, v44
	v_add_f32_e32 v44, v44, v44
	v_mul_f32_e32 v44, 0x3fb8aa3b, v44
	v_exp_f32_e32 v44, v44
	v_mul_f32_e32 v42, 0.5, v42
	v_add_f32_e32 v44, 1.0, v44
	v_div_scale_f32 v45, s[2:3], v44, v44, 2.0
	v_rcp_f32_e32 v46, v45
	s_nop 0
	v_fma_f32 v47, -v45, v46, 1.0
	v_fmac_f32_e32 v46, v47, v46
	v_div_scale_f32 v47, vcc, 2.0, v44, 2.0
	v_mul_f32_e32 v48, v47, v46
	v_fma_f32 v49, -v45, v48, v47
	v_fmac_f32_e32 v48, v49, v46
	v_fma_f32 v45, -v45, v48, v47
	v_div_fmas_f32 v45, v45, v46, v48
	v_div_fixup_f32 v44, v45, v44, 2.0
	v_sub_f32_e32 v44, 1.0, v44
	v_add_f32_e32 v44, 1.0, v44
	v_mul_f32_e32 v42, v42, v44
	v_bfe_u32 v44, v42, 16, 1
	v_add3_u32 v42, v42, v44, s31
	global_store_short_d16_hi v[40:41], v42, off
	v_or_b32_e32 v40, 35, v82
	v_mov_b32_e32 v41, v83
	v_lshlrev_b64 v[40:41], 9, v[40:41]
	v_lshl_add_u64 v[40:41], v[40:41], 0, v[50:51]
	v_lshlrev_b64 v[40:41], 1, v[40:41]
	v_lshl_add_u64 v[44:45], s[8:9], 0, v[40:41]
	v_lshl_add_u64 v[40:41], s[28:29], 0, v[40:41]
	s_waitcnt vmcnt(3)
	v_lshlrev_b32_e32 v42, 16, v211
	v_fmac_f32_e32 v43, v54, v42
	v_mul_f32_e32 v42, 0x3d372713, v43
	v_mul_f32_e32 v42, v43, v42
	v_fma_f32 v42, v43, v42, v43
	v_mul_f32_e32 v42, 0x3f4c422a, v42
	v_add_f32_e32 v42, v42, v42
	v_mul_f32_e32 v42, 0x3fb8aa3b, v42
	v_exp_f32_e32 v42, v42
	v_mul_f32_e32 v43, 0.5, v43
	v_add_f32_e32 v42, 1.0, v42
	v_div_scale_f32 v44, s[2:3], v42, v42, 2.0
	v_rcp_f32_e32 v45, v44
	s_nop 0
	v_fma_f32 v46, -v44, v45, 1.0
	v_fmac_f32_e32 v45, v46, v45
	v_div_scale_f32 v46, vcc, 2.0, v42, 2.0
	v_mul_f32_e32 v47, v46, v45
	v_fma_f32 v48, -v44, v47, v46
	v_fmac_f32_e32 v47, v48, v45
	v_fma_f32 v44, -v44, v47, v46
	v_div_fmas_f32 v44, v44, v45, v47
	v_div_fixup_f32 v42, v44, v42, 2.0
	v_sub_f32_e32 v42, 1.0, v42
	v_add_f32_e32 v42, 1.0, v42
	v_mul_f32_e32 v42, v43, v42
	v_bfe_u32 v43, v42, 16, 1
	v_add3_u32 v42, v42, v43, s31
	global_store_short_d16_hi v[40:41], v42, off
	v_mfma_f32_16x16x32_bf16 v[40:43], v[2:5], v[26:29], 0
	s_barrier
	v_mfma_f32_16x16x32_bf16 v[26:29], v[2:5], v[34:37], 0
	v_mfma_f32_16x16x32_bf16 v[2:5], v[2:5], v[6:9], 0
	s_nop 4
	v_mov_b32_e32 v34, v40
	s_nop 0
	v_mov_b32_e32 v35, v26
	v_mov_b32_e32 v26, v41
	v_mov_b32_e32 v36, v42
	v_mov_b32_e32 v37, v28
	v_mov_b32_e32 v40, v22
	v_mov_b32_e32 v41, v30
	v_mov_b32_e32 v30, v23
	v_mov_b32_e32 v22, v24
	v_mov_b32_e32 v23, v32
	ds_write2_b64 v108, v[36:37], v[22:23] offset0:128 offset1:144
	v_mov_b32_e32 v23, v14
	v_mov_b32_e32 v14, v19
	v_mov_b32_e32 v6, v10
	v_mov_b32_e32 v7, v2
	v_mov_b32_e32 v2, v11
	v_mov_b32_e32 v28, v43
	v_mov_b32_e32 v32, v25
	v_mov_b32_e32 v22, v18
	ds_write2_b64 v108, v[30:31], v[14:15] offset0:80 offset1:96
	v_mov_b32_e32 v14, v20
	v_mov_b32_e32 v15, v16
	v_mov_b32_e32 v16, v21
	ds_write2st64_b64 v99, v[6:7], v[2:3] offset0:8 offset1:9
	v_mov_b32_e32 v2, v12
	v_mov_b32_e32 v3, v4
	v_mov_b32_e32 v4, v13
	ds_write2_b64 v108, v[34:35], v[40:41] offset1:16
	ds_write2_b64 v108, v[22:23], v[26:27] offset0:32 offset1:64
	ds_write2_b64 v108, v[14:15], v[28:29] offset0:160 offset1:192
	ds_write2_b64 v108, v[32:33], v[16:17] offset0:208 offset1:224
	ds_write2st64_b64 v99, v[2:3], v[4:5] offset0:10 offset1:11
	s_waitcnt lgkmcnt(0)
	s_barrier
	ds_read_b64 v[2:3], v90 offset:4096
	v_xor_b32_e32 v4, 0x80000000, v39
	v_mov_b32_e32 v5, v38
	v_pk_mul_f32 v[4:5], v[0:1], v[4:5] op_sel_hi:[0,1]
	v_pk_fma_f32 v[4:5], v[84:85], v[38:39], v[4:5] op_sel_hi:[0,1,1]
	s_waitcnt lgkmcnt(0)
	v_pk_add_f32 v[2:3], v[4:5], v[2:3]
	ds_write2st64_b32 v98, v2, v3 offset1:1
	ds_read_b64 v[4:5], v90 offset:4608
	v_xor_b32_e32 v6, 0x80000000, v3
	v_mov_b32_e32 v7, v2
	v_pk_mul_f32 v[6:7], v[0:1], v[6:7] op_sel_hi:[0,1]
	v_pk_fma_f32 v[2:3], v[84:85], v[2:3], v[6:7] op_sel_hi:[0,1,1]
	s_waitcnt lgkmcnt(0)
	v_pk_add_f32 v[2:3], v[4:5], v[2:3]
	ds_write2_b32 v98, v2, v3 offset0:132 offset1:196
	ds_read_b64 v[4:5], v90 offset:5120
	v_xor_b32_e32 v6, 0x80000000, v3
	v_mov_b32_e32 v7, v2
	v_pk_mul_f32 v[6:7], v[0:1], v[6:7] op_sel_hi:[0,1]
	v_pk_fma_f32 v[2:3], v[84:85], v[2:3], v[6:7] op_sel_hi:[0,1,1]
	s_waitcnt lgkmcnt(0)
	v_pk_add_f32 v[2:3], v[4:5], v[2:3]
	ds_write2st64_b32 v78, v2, v3 offset0:4 offset1:5
	ds_read_b64 v[4:5], v90 offset:5632
	v_xor_b32_e32 v6, 0x80000000, v3
	v_mov_b32_e32 v7, v2
	v_pk_mul_f32 v[6:7], v[0:1], v[6:7] op_sel_hi:[0,1]
	v_pk_fma_f32 v[2:3], v[84:85], v[2:3], v[6:7] op_sel_hi:[0,1,1]
	s_waitcnt lgkmcnt(0)
	v_pk_add_f32 v[2:3], v[4:5], v[2:3]
	ds_write2st64_b32 v79, v2, v3 offset0:6 offset1:7
	ds_read_b64 v[4:5], v90 offset:6144
	v_xor_b32_e32 v6, 0x80000000, v3
	v_mov_b32_e32 v7, v2
	v_pk_mul_f32 v[6:7], v[0:1], v[6:7] op_sel_hi:[0,1]
	v_pk_fma_f32 v[2:3], v[84:85], v[2:3], v[6:7] op_sel_hi:[0,1,1]
	s_waitcnt lgkmcnt(0)
	v_pk_add_f32 v[2:3], v[4:5], v[2:3]
	ds_write2st64_b32 v80, v2, v3 offset0:8 offset1:9
	ds_read_b64 v[4:5], v90 offset:6656
	v_xor_b32_e32 v6, 0x80000000, v3
	v_mov_b32_e32 v7, v2
	v_pk_mul_f32 v[6:7], v[0:1], v[6:7] op_sel_hi:[0,1]
	v_pk_fma_f32 v[2:3], v[84:85], v[2:3], v[6:7] op_sel_hi:[0,1,1]
	s_waitcnt lgkmcnt(0)
	v_pk_add_f32 v[2:3], v[4:5], v[2:3]
	ds_write2st64_b32 v81, v2, v3 offset0:10 offset1:11
	ds_read_b64 v[4:5], v90 offset:7168
	v_xor_b32_e32 v6, 0x80000000, v3
	v_mov_b32_e32 v7, v2
	v_pk_mul_f32 v[6:7], v[0:1], v[6:7] op_sel_hi:[0,1]
	v_pk_fma_f32 v[2:3], v[84:85], v[2:3], v[6:7] op_sel_hi:[0,1,1]
	s_waitcnt lgkmcnt(0)
; __device__ __forceinline__ void s5_pass2_item(PP p, unsigned char* shm, int item, int l) {
;     ...
; #pragma unroll
;         for (int t = 0; t < 16; ++t) { s5_rec(q, *(const f32x2*)(buL + (t * 64 + lane) * 2), x); xs[t * 132 + lane] = x.x; xs[t * 132 + 64 + lane] = x.y; }
;         __syncthreads();
	v_pk_add_f32 v[2:3], v[4:5], v[2:3]
	ds_write2st64_b32 v86, v2, v3 offset0:12 offset1:13
	ds_read_b64 v[4:5], v90 offset:7680
	v_xor_b32_e32 v6, 0x80000000, v3
	v_mov_b32_e32 v7, v2
	v_pk_mul_f32 v[6:7], v[0:1], v[6:7] op_sel_hi:[0,1]
	v_pk_fma_f32 v[2:3], v[84:85], v[2:3], v[6:7] op_sel_hi:[0,1,1]
	s_waitcnt lgkmcnt(0)
	v_pk_add_f32 v[2:3], v[4:5], v[2:3]
	ds_write2st64_b32 v87, v2, v3 offset0:14 offset1:15
	ds_read_b64 v[4:5], v90 offset:8192
	v_xor_b32_e32 v6, 0x80000000, v3
	v_mov_b32_e32 v7, v2
	v_pk_mul_f32 v[6:7], v[0:1], v[6:7] op_sel_hi:[0,1]
	v_pk_fma_f32 v[2:3], v[84:85], v[2:3], v[6:7] op_sel_hi:[0,1,1]
	s_waitcnt lgkmcnt(0)
	v_pk_add_f32 v[2:3], v[4:5], v[2:3]
	ds_write2st64_b32 v100, v2, v3 offset0:16 offset1:17
	ds_read_b64 v[4:5], v90 offset:8704
	v_xor_b32_e32 v6, 0x80000000, v3
	v_mov_b32_e32 v7, v2
	v_pk_mul_f32 v[6:7], v[0:1], v[6:7] op_sel_hi:[0,1]
	v_pk_fma_f32 v[2:3], v[84:85], v[2:3], v[6:7] op_sel_hi:[0,1,1]
	s_waitcnt lgkmcnt(0)
	v_pk_add_f32 v[2:3], v[4:5], v[2:3]
	ds_write2st64_b32 v101, v2, v3 offset0:18 offset1:19
	ds_read_b64 v[4:5], v90 offset:9216
	v_xor_b32_e32 v6, 0x80000000, v3
	v_mov_b32_e32 v7, v2
	v_pk_mul_f32 v[6:7], v[0:1], v[6:7] op_sel_hi:[0,1]
	v_pk_fma_f32 v[2:3], v[84:85], v[2:3], v[6:7] op_sel_hi:[0,1,1]
	s_waitcnt lgkmcnt(0)
	v_pk_add_f32 v[2:3], v[4:5], v[2:3]
	ds_write2st64_b32 v102, v2, v3 offset0:20 offset1:21
	ds_read_b64 v[4:5], v90 offset:9728
	v_xor_b32_e32 v6, 0x80000000, v3
	v_mov_b32_e32 v7, v2
	v_pk_mul_f32 v[6:7], v[0:1], v[6:7] op_sel_hi:[0,1]
	v_pk_fma_f32 v[2:3], v[84:85], v[2:3], v[6:7] op_sel_hi:[0,1,1]
	s_waitcnt lgkmcnt(0)
	v_pk_add_f32 v[2:3], v[4:5], v[2:3]
	ds_write2st64_b32 v103, v2, v3 offset0:22 offset1:23
	ds_read_b64 v[4:5], v90 offset:10240
	v_xor_b32_e32 v6, 0x80000000, v3
	v_mov_b32_e32 v7, v2
	v_pk_mul_f32 v[6:7], v[0:1], v[6:7] op_sel_hi:[0,1]
	v_pk_fma_f32 v[2:3], v[84:85], v[2:3], v[6:7] op_sel_hi:[0,1,1]
	s_waitcnt lgkmcnt(0)
	v_pk_add_f32 v[2:3], v[4:5], v[2:3]
	ds_write2st64_b32 v104, v2, v3 offset0:24 offset1:25
	ds_read_b64 v[4:5], v90 offset:10752
	v_xor_b32_e32 v6, 0x80000000, v3
	v_mov_b32_e32 v7, v2
	v_pk_mul_f32 v[6:7], v[0:1], v[6:7] op_sel_hi:[0,1]
	v_pk_fma_f32 v[2:3], v[84:85], v[2:3], v[6:7] op_sel_hi:[0,1,1]
	s_waitcnt lgkmcnt(0)
	v_pk_add_f32 v[2:3], v[4:5], v[2:3]
	ds_write2st64_b32 v105, v2, v3 offset0:26 offset1:27
	ds_read_b64 v[4:5], v90 offset:11264
	v_xor_b32_e32 v6, 0x80000000, v3
	v_mov_b32_e32 v7, v2
	v_pk_mul_f32 v[6:7], v[0:1], v[6:7] op_sel_hi:[0,1]
	v_pk_fma_f32 v[2:3], v[84:85], v[2:3], v[6:7] op_sel_hi:[0,1,1]
	s_waitcnt lgkmcnt(0)
	v_pk_add_f32 v[2:3], v[4:5], v[2:3]
	ds_write2st64_b32 v106, v2, v3 offset0:28 offset1:29
	ds_read_b64 v[4:5], v90 offset:11776
	v_xor_b32_e32 v6, 0x80000000, v3
	v_mov_b32_e32 v7, v2
	v_pk_mul_f32 v[6:7], v[0:1], v[6:7] op_sel_hi:[0,1]
	v_pk_fma_f32 v[2:3], v[84:85], v[2:3], v[6:7] op_sel_hi:[0,1,1]
	s_waitcnt lgkmcnt(0)
	v_pk_add_f32 v[2:3], v[4:5], v[2:3]
	ds_write2st64_b32 v107, v2, v3 offset0:30 offset1:31
	s_waitcnt lgkmcnt(0)
	s_barrier
; __device__ __forceinline__ float bf2f(bf16_t v) { return __uint_as_float(((unsigned)v) << 16); }
; __device__ __forceinline__ bf16_t f2bf(float f) { unsigned u = __float_as_uint(f); u += 0x7FFFu + ((u >> 16) & 1u); return (bf16_t)(u >> 16); }
; __device__ __forceinline__ void s5_pass2_item(PP p, unsigned char* shm, int item, int l) {
;     ...
;         f32x4 y0 = (f32x4){0.f, 0.f, 0.f, 0.f}, y1 = y0;
;         const f32x4* xrow = (const f32x4*)(xs + cc * 132 + quad * 32);
; #pragma unroll
;         for (int i = 0; i < 8; ++i) { const f32x4 xv = xrow[i];
;             y0 = __builtin_amdgcn_mfma_f32_16x16x4f32(xv[0], cmr[4 * i + 0], y0, 0, 0, 0);
;             y1 = __builtin_amdgcn_mfma_f32_16x16x4f32(xv[1], cmr[4 * i + 1], y1, 0, 0, 0);
;             y0 = __builtin_amdgcn_mfma_f32_16x16x4f32(xv[2], cmr[4 * i + 2], y0, 0, 0, 0);
;             y1 = __builtin_amdgcn_mfma_f32_16x16x4f32(xv[3], cmr[4 * i + 3], y1, 0, 0, 0); }
;         const f32x4 y = y0 + y1;
; #pragma unroll
;         for (int r = 0; r < 4; ++r) { const int tl = sc * 16 + quad * 4 + r;
;             const float v = y[r] + dsk * bf2f(proj[PJ_UA + (row0 + tl) * 512 + g * 16 + cc]);
;             const float z = 0.7978845608028654f * (v + 0.044715f * v * v * v);
;             const float th = 1.0f - 2.0f / (__expf(2.0f * z) + 1.0f);
;             Gout[(row0 + tl) * 512 + g * 16 + cc] = f2bf(0.5f * v * (1.0f + th)); }
;         __syncthreads();
;     }
	v_or_b32_e32 v216, 48, v82
	v_mov_b32_e32 v217, v83
	v_lshlrev_b64 v[216:217], 9, v[216:217]
	v_lshl_add_u64 v[216:217], v[216:217], 0, v[50:51]
	v_lshlrev_b64 v[216:217], 1, v[216:217]
	v_lshl_add_u64 v[216:217], s[8:9], 0, v[216:217]
	global_load_ushort v212, v[216:217], off
	global_load_ushort v213, v[216:217], off offset:1024
	global_load_ushort v214, v[216:217], off offset:2048
	global_load_ushort v215, v[216:217], off offset:3072
	ds_read_b128 v[2:5], v89
	ds_read_b128 v[6:9], v89 offset:16
	ds_read_b128 v[10:13], v89 offset:32
	ds_read_b128 v[14:17], v89 offset:48
	s_waitcnt lgkmcnt(3)
	v_mfma_f32_16x16x4_f32 v[18:21], v2, v97, 0
	v_mfma_f32_16x16x4_f32 v[22:25], v3, v96, 0
	v_mfma_f32_16x16x4_f32 v[18:21], v4, v95, v[18:21]
	v_mfma_f32_16x16x4_f32 v[2:5], v5, v94, v[22:25]
	s_waitcnt lgkmcnt(2)
	v_mfma_f32_16x16x4_f32 v[18:21], v6, v93, v[18:21]
	v_mfma_f32_16x16x4_f32 v[2:5], v7, v92, v[2:5]
	v_mfma_f32_16x16x4_f32 v[18:21], v8, v91, v[18:21]
	v_mfma_f32_16x16x4_f32 v[2:5], v9, v88, v[2:5]
	s_waitcnt lgkmcnt(1)
	v_mfma_f32_16x16x4_f32 v[6:9], v10, v85, v[18:21]
	v_mfma_f32_16x16x4_f32 v[2:5], v11, v55, v[2:5]
	v_mfma_f32_16x16x4_f32 v[6:9], v12, v56, v[6:9]
	v_mfma_f32_16x16x4_f32 v[2:5], v13, v57, v[2:5]
	ds_read_b128 v[10:13], v89 offset:64
	s_waitcnt lgkmcnt(1)
	v_mfma_f32_16x16x4_f32 v[6:9], v14, v58, v[6:9]
	v_mfma_f32_16x16x4_f32 v[2:5], v15, v59, v[2:5]
	v_mfma_f32_16x16x4_f32 v[6:9], v16, v60, v[6:9]
	v_mfma_f32_16x16x4_f32 v[2:5], v17, v61, v[2:5]
	s_waitcnt lgkmcnt(0)
	v_mfma_f32_16x16x4_f32 v[6:9], v10, v62, v[6:9]
	v_mfma_f32_16x16x4_f32 v[2:5], v11, v63, v[2:5]
	v_mfma_f32_16x16x4_f32 v[6:9], v12, v64, v[6:9]
	v_mfma_f32_16x16x4_f32 v[2:5], v13, v65, v[2:5]
	ds_read_b128 v[10:13], v89 offset:80
	s_waitcnt lgkmcnt(0)
	v_mfma_f32_16x16x4_f32 v[6:9], v10, v66, v[6:9]
	v_mfma_f32_16x16x4_f32 v[2:5], v11, v67, v[2:5]
	v_mfma_f32_16x16x4_f32 v[6:9], v12, v68, v[6:9]
	v_mfma_f32_16x16x4_f32 v[2:5], v13, v69, v[2:5]
	ds_read_b128 v[10:13], v89 offset:96
	s_waitcnt lgkmcnt(0)
	v_mfma_f32_16x16x4_f32 v[6:9], v10, v70, v[6:9]
	v_mfma_f32_16x16x4_f32 v[2:5], v11, v71, v[2:5]
	v_mfma_f32_16x16x4_f32 v[6:9], v12, v72, v[6:9]
	v_mfma_f32_16x16x4_f32 v[2:5], v13, v73, v[2:5]
	ds_read_b128 v[10:13], v89 offset:112
	s_waitcnt lgkmcnt(0)
	v_mfma_f32_16x16x4_f32 v[6:9], v10, v74, v[6:9]
	v_mfma_f32_16x16x4_f32 v[2:5], v11, v75, v[2:5]
	v_mfma_f32_16x16x4_f32 v[6:9], v12, v76, v[6:9]
	v_mfma_f32_16x16x4_f32 v[10:13], v13, v77, v[2:5]
	s_nop 9
	v_pk_add_f32 v[4:5], v[6:7], v[10:11]
	v_or_b32_e32 v6, 48, v82
	v_mov_b32_e32 v7, v83
	v_lshlrev_b64 v[6:7], 9, v[6:7]
	v_lshl_add_u64 v[6:7], v[6:7], 0, v[50:51]
	v_lshlrev_b64 v[6:7], 1, v[6:7]
	v_pk_add_f32 v[2:3], v[8:9], v[12:13]
	v_lshl_add_u64 v[8:9], s[8:9], 0, v[6:7]
	v_lshl_add_u64 v[6:7], s[28:29], 0, v[6:7]
	s_waitcnt vmcnt(3)
	v_lshlrev_b32_e32 v0, 16, v212
	v_fma_f32 v0, v54, v0, v4
	v_mul_f32_e32 v4, 0x3d372713, v0
	v_mul_f32_e32 v4, v0, v4
	v_fma_f32 v4, v0, v4, v0
	v_mul_f32_e32 v4, 0x3f4c422a, v4
	v_add_f32_e32 v4, v4, v4
	v_mul_f32_e32 v4, 0x3fb8aa3b, v4
	v_exp_f32_e32 v4, v4
	v_mul_f32_e32 v0, 0.5, v0
	v_add_f32_e32 v4, 1.0, v4
	v_div_scale_f32 v8, s[2:3], v4, v4, 2.0
	v_rcp_f32_e32 v9, v8
	s_nop 0
	v_fma_f32 v10, -v8, v9, 1.0
	v_fmac_f32_e32 v9, v10, v9
	v_div_scale_f32 v10, vcc, 2.0, v4, 2.0
	v_mul_f32_e32 v11, v10, v9
	v_fma_f32 v12, -v8, v11, v10
	v_fmac_f32_e32 v11, v12, v9
	v_fma_f32 v8, -v8, v11, v10
	v_div_fmas_f32 v8, v8, v9, v11
	v_div_fixup_f32 v4, v8, v4, 2.0
	v_sub_f32_e32 v4, 1.0, v4
	v_add_f32_e32 v4, 1.0, v4
	v_mul_f32_e32 v0, v0, v4
	v_bfe_u32 v4, v0, 16, 1
	v_add3_u32 v0, v0, v4, s31
	global_store_short_d16_hi v[6:7], v0, off
	v_or_b32_e32 v6, 49, v82
	v_mov_b32_e32 v7, v83
	v_lshlrev_b64 v[6:7], 9, v[6:7]
	v_lshl_add_u64 v[6:7], v[6:7], 0, v[50:51]
	v_lshlrev_b64 v[6:7], 1, v[6:7]
	v_lshl_add_u64 v[8:9], s[8:9], 0, v[6:7]
	s_waitcnt vmcnt(3)
	v_lshlrev_b32_e32 v0, 16, v213
	v_fmac_f32_e32 v5, v54, v0
	v_mul_f32_e32 v0, 0x3d372713, v5
	v_mul_f32_e32 v0, v5, v0
	v_fma_f32 v0, v5, v0, v5
	v_mul_f32_e32 v0, 0x3f4c422a, v0
	v_add_f32_e32 v0, v0, v0
	v_mul_f32_e32 v0, 0x3fb8aa3b, v0
	v_exp_f32_e32 v0, v0
	s_nop 0
	v_add_f32_e32 v0, 1.0, v0
	v_div_scale_f32 v4, s[2:3], v0, v0, 2.0
	v_rcp_f32_e32 v8, v4
	s_nop 0
	v_fma_f32 v9, -v4, v8, 1.0
	v_fmac_f32_e32 v8, v9, v8
	v_div_scale_f32 v9, vcc, 2.0, v0, 2.0
	v_mul_f32_e32 v10, v9, v8
	v_fma_f32 v11, -v4, v10, v9
	v_fmac_f32_e32 v10, v11, v8
	v_fma_f32 v4, -v4, v10, v9
	v_div_fmas_f32 v4, v4, v8, v10
	v_div_fixup_f32 v0, v4, v0, 2.0
	v_sub_f32_e32 v0, 1.0, v0
	v_mul_f32_e32 v4, 0.5, v5
	v_add_f32_e32 v0, 1.0, v0
	v_mul_f32_e32 v0, v4, v0
	v_bfe_u32 v4, v0, 16, 1
	v_add3_u32 v0, v0, v4, s31
	v_lshl_add_u64 v[4:5], s[28:29], 0, v[6:7]
	global_store_short_d16_hi v[4:5], v0, off
	v_or_b32_e32 v4, 50, v82
	v_mov_b32_e32 v5, v83
	v_lshlrev_b64 v[4:5], 9, v[4:5]
	v_lshl_add_u64 v[4:5], v[4:5], 0, v[50:51]
	v_lshlrev_b64 v[4:5], 1, v[4:5]
	v_lshl_add_u64 v[6:7], s[8:9], 0, v[4:5]
	v_lshl_add_u64 v[4:5], s[28:29], 0, v[4:5]
	v_or_b32_e32 v82, 51, v82
	s_waitcnt vmcnt(3)
	v_lshlrev_b32_e32 v0, 16, v214
	v_fma_f32 v0, v54, v0, v2
	v_mul_f32_e32 v2, 0x3d372713, v0
	v_mul_f32_e32 v2, v0, v2
	v_fma_f32 v2, v0, v2, v0
	v_mul_f32_e32 v2, 0x3f4c422a, v2
	v_add_f32_e32 v2, v2, v2
	v_mul_f32_e32 v2, 0x3fb8aa3b, v2
	v_exp_f32_e32 v2, v2
	v_mul_f32_e32 v0, 0.5, v0
	v_add_f32_e32 v2, 1.0, v2
	v_div_scale_f32 v6, s[2:3], v2, v2, 2.0
	v_rcp_f32_e32 v7, v6
	s_nop 0
	v_fma_f32 v8, -v6, v7, 1.0
	v_fmac_f32_e32 v7, v8, v7
	v_div_scale_f32 v8, vcc, 2.0, v2, 2.0
	v_mul_f32_e32 v9, v8, v7
	v_fma_f32 v10, -v6, v9, v8
	v_fmac_f32_e32 v9, v10, v7
	v_fma_f32 v6, -v6, v9, v8
	v_div_fmas_f32 v6, v6, v7, v9
	v_div_fixup_f32 v2, v6, v2, 2.0
	v_sub_f32_e32 v2, 1.0, v2
	v_add_f32_e32 v2, 1.0, v2
	v_mul_f32_e32 v0, v0, v2
	v_bfe_u32 v2, v0, 16, 1
	v_add3_u32 v0, v0, v2, s31
	global_store_short_d16_hi v[4:5], v0, off
	v_lshlrev_b64 v[4:5], 9, v[82:83]
	v_lshl_add_u64 v[4:5], v[4:5], 0, v[50:51]
	v_lshlrev_b64 v[4:5], 1, v[4:5]
	v_lshl_add_u64 v[6:7], s[8:9], 0, v[4:5]
	s_waitcnt vmcnt(3)
	v_lshlrev_b32_e32 v0, 16, v215
	v_fmac_f32_e32 v3, v54, v0
	v_mul_f32_e32 v0, 0x3d372713, v3
	v_mul_f32_e32 v0, v3, v0
	v_fma_f32 v0, v3, v0, v3
	v_mul_f32_e32 v0, 0x3f4c422a, v0
	v_add_f32_e32 v0, v0, v0
	v_mul_f32_e32 v0, 0x3fb8aa3b, v0
	v_exp_f32_e32 v0, v0
	s_nop 0
	v_add_f32_e32 v0, 1.0, v0
	v_div_scale_f32 v2, s[2:3], v0, v0, 2.0
	v_rcp_f32_e32 v6, v2
	s_nop 0
	v_fma_f32 v7, -v2, v6, 1.0
	v_fmac_f32_e32 v6, v7, v6
	v_div_scale_f32 v7, vcc, 2.0, v0, 2.0
	v_mul_f32_e32 v8, v7, v6
	v_fma_f32 v9, -v2, v8, v7
	v_fmac_f32_e32 v8, v9, v6
	v_fma_f32 v2, -v2, v8, v7
	v_div_fmas_f32 v2, v2, v6, v8
	v_div_fixup_f32 v0, v2, v0, 2.0
	v_sub_f32_e32 v0, 1.0, v0
	v_mul_f32_e32 v2, 0.5, v3
	v_add_f32_e32 v0, 1.0, v0
	v_mul_f32_e32 v0, v2, v0
	v_bfe_u32 v2, v0, 16, 1
	v_add3_u32 v0, v0, v2, s31
	v_lshl_add_u64 v[2:3], s[28:29], 0, v[4:5]
	global_store_short_d16_hi v[2:3], v0, off
	s_barrier
	s_cbranch_scc1 .LBB0_718
